# combo28 with forward-substitution bulk A reads shared between the two column groups of a 16-lane row through a DPP row_ror:8 operand (half the LDS reads)
# baseline (speedup 1.0000x reference)
; #define LAS __attribute__((address_space(3)))
; __device__ __forceinline__ bf16_t f2bf(float f) { return (bf16_t)(cvt_pk_bf16(f, 0.f) & 0xffffu); }
; __device__ __forceinline__ void dn_prep(const Params& p, LAS unsigned char* lds) {
;     ...
;         if (wid == 0) {
;             float T[64];
;             int zoff; asm volatile("v_mov_b32 %0, 0" : "=v"(zoff));
;             const LAS float* Asz = As + zoff;
;             const float bc = beta_s[lane], wcf = bc * __expf(G_s[lane]);
;             int lo2 = lane; asm volatile("" : "+v"(lo2));
;             LAS bf16_t* tub = Tu + lo2; LAS bf16_t* twb = Tw + lo2;
;             f32x4 rlo[2][8], rhi[8];
;             T[0] = (lane == 0) ? 1.f : 0.f;
;             tub[0] = f2bf(T[0] * bc); twb[0] = f2bf(T[0] * wcf);
;             rlo[1][0] = *(const LAS f32x4*)(Asz + 68);
.LBB0_375:
	s_or_b64 exec, exec, s[24:25]
	s_waitcnt lgkmcnt(0)
	s_barrier
	s_and_b64 s[0:1], s[2:3], s[68:69]
	s_xor_b64 s[0:1], s[0:1], -1
	s_and_saveexec_b64 s[6:7], s[0:1]
	s_xor_b64 s[24:25], exec, s[6:7]
	s_cbranch_execz .LBB0_379
	s_mov_b64 s[28:29], exec
	s_and_b64 vcc, exec, s[68:69]
	s_cbranch_vccnz .LBB0_378
	v_readfirstlane_b32 s1, v184
	v_and_b32_e32 v7, 63, v184
	s_nop 3
	s_lshr_b32 s1, s1, 6
	v_and_b32_e32 v6, 7, v7
	v_lshrrev_b32_e32 v7, 3, v7
	s_lshl_b32 s32, s1, 3
	s_movk_i32 s89, 0x90
	s_mov_b32 s6, 0x02020202
	s_mov_b32 s7, 0x02020202
	s_mov_b32 s68, 0x04040404
	s_mov_b32 s69, 0x04040404
	s_mov_b32 s92, 0x08080808
	s_mov_b32 s93, 0x08080808
	s_mov_b32 s94, 0x10101010
	s_mov_b32 s95, 0x10101010
	s_mov_b32 s96, 0x20202020
	s_mov_b32 s97, 0x20202020
	s_mov_b32 s98, 0x40404040
	s_mov_b32 s99, 0x40404040
	s_mov_b32 s100, 0x80808080
	s_mov_b32 s101, 0x80808080
	v_add_u32_e32 v128, s32, v7
	v_cmp_eq_u32_e32 vcc, 0, v7
	s_nop 1
	v_cndmask_b32_e64 v16, 0, 1.0, vcc
	v_cmp_eq_u32_e32 vcc, 1, v7
	s_nop 1
	v_cndmask_b32_e64 v17, 0, 1.0, vcc
	v_cmp_eq_u32_e32 vcc, 2, v7
	s_nop 1
	v_cndmask_b32_e64 v18, 0, 1.0, vcc
	v_cmp_eq_u32_e32 vcc, 3, v7
	s_nop 1
	v_cndmask_b32_e64 v19, 0, 1.0, vcc
	v_cmp_eq_u32_e32 vcc, 4, v7
	s_nop 1
	v_cndmask_b32_e64 v20, 0, 1.0, vcc
	v_cmp_eq_u32_e32 vcc, 5, v7
	s_nop 1
	v_cndmask_b32_e64 v21, 0, 1.0, vcc
	v_cmp_eq_u32_e32 vcc, 6, v7
	s_nop 1
	v_cndmask_b32_e64 v22, 0, 1.0, vcc
	v_cmp_eq_u32_e32 vcc, 7, v7
	s_nop 1
	v_cndmask_b32_e64 v23, 0, 1.0, vcc
	v_lshl_add_u32 v0, v6, 2, s13
	v_and_b32_e32 v48, 1, v7
	v_lshl_add_u32 v49, v48, 5, v0
	v_mov_b32_e32 v42, 0
	v_mov_b32_e32 v43, 0
	v_mov_b32_e32 v44, 0
	v_mov_b32_e32 v45, 0
	v_mov_b32_e32 v46, 0
	v_mov_b32_e32 v47, 0
	v_mov_b32_e32 v1, s13
	v_mov_b32_e32 v40, 0x110
	v_mad_u32_u24 v40, v6, v40, v1
	v_lshlrev_b32_e32 v2, 1, v128
	v_mad_u32_u24 v2, v6, s89, v2
	v_add_u32_e32 v3, 0x18000, v2
	v_add_u32_e32 v2, 0x15c00, v2
	v_lshlrev_b32_e32 v129, 2, v128
	v_add_u32_e32 v129, 0x1a400, v129
	ds_read_b32 v4, v129
	ds_read_b32 v5, v129 offset:256
	ds_read_b128 v[32:35], v40 offset:0
	ds_read_b128 v[36:39], v40 offset:16
	v_mov_b32_e32 v8, 0
	v_mov_b32_e32 v9, 0
	v_mov_b32_e32 v10, 0
	v_mov_b32_e32 v11, 0
	v_mov_b32_e32 v12, 0
	v_mov_b32_e32 v13, 0
	v_mov_b32_e32 v14, 0
	v_mov_b32_e32 v15, 0
	v_mov_b32_e32 v6, 0
	s_mov_b32 s91, 1.0
	s_waitcnt lgkmcnt(2)
	v_mul_f32_e32 v5, 0x3fb8aa3b, v5
	v_exp_f32_e32 v5, v5
	s_nop 0
	v_mul_f32_e32 v5, v4, v5

; #define LAS __attribute__((address_space(3)))
; __device__ __forceinline__ bf16_t f2bf(float f) { return (bf16_t)(cvt_pk_bf16(f, 0.f) & 0xffffu); }
; __device__ __forceinline__ void dn_prep(const Params& p, LAS unsigned char* lds) {
;     ...
;             for (int i = 1; i < 64; ++i) {
; #pragma unroll
;                 for (int j4 = 8; j4 < (i + 3) / 4; ++j4) rhi[j4 - 8] = *(const LAS f32x4*)(Asz + i * 68 + j4 * 4);
;                 if (i + 1 < 64) {
; #pragma unroll
;                     for (int j4 = 0; j4 < ((i + 4) / 4 < 8 ? (i + 4) / 4 : 8); ++j4) rlo[(i + 1) & 1][j4] = *(const LAS f32x4*)(Asz + (i + 1) * 68 + j4 * 4);
;                 }
;                 float a0 = (lane == i) ? 1.f : 0.f, a1 = 0.f, a2 = 0.f, a3 = 0.f;
; #pragma unroll
;                 for (int j4 = 0; j4 < (i + 3) / 4; ++j4) {
;                     const f32x4 av = (j4 < 8) ? rlo[i & 1][j4 & 7] : rhi[(j4 - 8) & 7];
;                     if (j4 * 4 + 0 < i) a0 -= av[0] * T[j4 * 4 + 0];
;                     if (j4 * 4 + 1 < i) a1 -= av[1] * T[j4 * 4 + 1];
;                     if (j4 * 4 + 2 < i) a2 -= av[2] * T[j4 * 4 + 2];
;                     if (j4 * 4 + 3 < i) a3 -= av[3] * T[j4 * 4 + 3];
;                 }
;                 T[i] = (a0 + a1) + (a2 + a3);
;                 tub[i * 72] = f2bf(T[i] * bc); twb[i * 72] = f2bf(T[i] * wcf);
.Lfs_b1:
	s_cmp_gt_u32 s1, 1
	s_cbranch_scc1 .Lfs_z1
	s_waitcnt lgkmcnt(4)
	v_mul_f32_e32 v24, v72, v8
	v_mul_f32_e32 v25, v79, v8
	v_mul_f32_e32 v26, v86, v8
	v_mul_f32_e32 v27, v93, v8
	v_mul_f32_e32 v28, v100, v8
	v_mul_f32_e32 v29, v107, v8
	v_mul_f32_e32 v30, v114, v8
	v_mul_f32_e32 v31, v121, v8
	v_add_f32_dpp v24, v24, v24 quad_perm:[1,0,3,2] row_mask:0xf bank_mask:0xf bound_ctrl:1
	v_add_f32_dpp v25, v25, v25 quad_perm:[1,0,3,2] row_mask:0xf bank_mask:0xf bound_ctrl:1
	v_add_f32_dpp v26, v26, v26 quad_perm:[1,0,3,2] row_mask:0xf bank_mask:0xf bound_ctrl:1
	v_add_f32_dpp v27, v27, v27 quad_perm:[1,0,3,2] row_mask:0xf bank_mask:0xf bound_ctrl:1
	v_add_f32_dpp v28, v28, v28 quad_perm:[1,0,3,2] row_mask:0xf bank_mask:0xf bound_ctrl:1
	v_add_f32_dpp v29, v29, v29 quad_perm:[1,0,3,2] row_mask:0xf bank_mask:0xf bound_ctrl:1
	v_add_f32_dpp v30, v30, v30 quad_perm:[1,0,3,2] row_mask:0xf bank_mask:0xf bound_ctrl:1
	v_add_f32_dpp v31, v31, v31 quad_perm:[1,0,3,2] row_mask:0xf bank_mask:0xf bound_ctrl:1
	v_add_f32_dpp v24, v24, v24 quad_perm:[2,3,0,1] row_mask:0xf bank_mask:0xf bound_ctrl:1
	v_add_f32_dpp v25, v25, v25 quad_perm:[2,3,0,1] row_mask:0xf bank_mask:0xf bound_ctrl:1
	v_add_f32_dpp v26, v26, v26 quad_perm:[2,3,0,1] row_mask:0xf bank_mask:0xf bound_ctrl:1
	v_add_f32_dpp v27, v27, v27 quad_perm:[2,3,0,1] row_mask:0xf bank_mask:0xf bound_ctrl:1
	v_add_f32_dpp v28, v28, v28 quad_perm:[2,3,0,1] row_mask:0xf bank_mask:0xf bound_ctrl:1
	v_add_f32_dpp v29, v29, v29 quad_perm:[2,3,0,1] row_mask:0xf bank_mask:0xf bound_ctrl:1
	v_add_f32_dpp v30, v30, v30 quad_perm:[2,3,0,1] row_mask:0xf bank_mask:0xf bound_ctrl:1
	v_add_f32_dpp v31, v31, v31 quad_perm:[2,3,0,1] row_mask:0xf bank_mask:0xf bound_ctrl:1
	v_add_f32_dpp v24, v24, v24 row_half_mirror row_mask:0xf bank_mask:0xf bound_ctrl:1
	v_add_f32_dpp v25, v25, v25 row_half_mirror row_mask:0xf bank_mask:0xf bound_ctrl:1
	v_add_f32_dpp v26, v26, v26 row_half_mirror row_mask:0xf bank_mask:0xf bound_ctrl:1
	v_add_f32_dpp v27, v27, v27 row_half_mirror row_mask:0xf bank_mask:0xf bound_ctrl:1
	v_add_f32_dpp v28, v28, v28 row_half_mirror row_mask:0xf bank_mask:0xf bound_ctrl:1
	v_add_f32_dpp v29, v29, v29 row_half_mirror row_mask:0xf bank_mask:0xf bound_ctrl:1
	v_add_f32_dpp v30, v30, v30 row_half_mirror row_mask:0xf bank_mask:0xf bound_ctrl:1
	v_add_f32_dpp v31, v31, v31 row_half_mirror row_mask:0xf bank_mask:0xf bound_ctrl:1
	v_fma_f32 v24, v16, s91, -v24
	v_fma_f32 v25, v17, s91, -v25
	v_fma_f32 v26, v18, s91, -v26
	v_fma_f32 v27, v19, s91, -v27
	v_fma_f32 v28, v20, s91, -v28
	v_fma_f32 v29, v21, s91, -v29
	v_fma_f32 v30, v22, s91, -v30
	v_fma_f32 v31, v23, s91, -v31
	s_waitcnt lgkmcnt(0)
	ds_read_b32 v72, v49 offset:4352
	ds_read_b32 v79, v49 offset:4624
	ds_read_b32 v86, v49 offset:4896
	ds_read_b32 v93, v49 offset:5168
	ds_read_b32 v100, v49 offset:5440
	ds_read_b32 v107, v49 offset:5712
	ds_read_b32 v114, v49 offset:5984
	ds_read_b32 v121, v49 offset:6256
	v_mov_b32_e32 v9, v24
	v_cndmask_b32_e64 v9, v9, v25, s[6:7]
	v_cndmask_b32_e64 v9, v9, v26, s[68:69]
	v_cndmask_b32_e64 v9, v9, v27, s[92:93]
	v_cndmask_b32_e64 v9, v9, v28, s[94:95]
	v_cndmask_b32_e64 v9, v9, v29, s[96:97]
	v_cndmask_b32_e64 v9, v9, v30, s[98:99]
	v_cndmask_b32_e64 v9, v9, v31, s[100:101]
	s_nop 1
	v_mov_b32_dpp v41, v9 quad_perm:[0,0,0,0] row_mask:0xf bank_mask:0xf
	s_nop 1
	v_mov_b32_dpp v41, v41 row_half_mirror row_mask:0xf bank_mask:0xa
	v_fma_f32 v9, -v32, v41, v9
	s_nop 1
	v_mov_b32_dpp v41, v9 quad_perm:[1,1,1,1] row_mask:0xf bank_mask:0xf
	s_nop 1
	v_mov_b32_dpp v41, v41 row_half_mirror row_mask:0xf bank_mask:0xa
	v_fma_f32 v9, -v33, v41, v9
	s_nop 1
	v_mov_b32_dpp v41, v9 quad_perm:[2,2,2,2] row_mask:0xf bank_mask:0xf
	s_nop 1
	v_mov_b32_dpp v41, v41 row_half_mirror row_mask:0xf bank_mask:0xa
	v_fma_f32 v9, -v34, v41, v9
	s_nop 1
	v_mov_b32_dpp v41, v9 quad_perm:[3,3,3,3] row_mask:0xf bank_mask:0xf
	s_nop 1
	v_mov_b32_dpp v41, v41 row_half_mirror row_mask:0xf bank_mask:0xa
	v_fma_f32 v9, -v35, v41, v9
	s_nop 1
	v_mov_b32_dpp v41, v9 quad_perm:[0,0,0,0] row_mask:0xf bank_mask:0xf
	v_fma_f32 v9, -v36, v41, v9
	s_nop 1
	v_mov_b32_dpp v41, v9 quad_perm:[1,1,1,1] row_mask:0xf bank_mask:0xf
	v_fma_f32 v9, -v37, v41, v9
	s_nop 1
	v_mov_b32_dpp v41, v9 quad_perm:[2,2,2,2] row_mask:0xf bank_mask:0xf
	v_fma_f32 v9, -v38, v41, v9
	ds_read_b128 v[32:35], v40 offset:4416
	ds_read_b128 v[36:39], v40 offset:4432
	v_mul_f32_e32 v128, v4, v9
	v_mul_f32_e32 v129, v5, v9
	v_cvt_pk_bf16_f32 v128, v128, v128
	v_cvt_pk_bf16_f32 v129, v129, v129
	ds_write_b16 v2, v128 offset:1152
	ds_write_b16 v3, v129 offset:1152
	s_mov_b32 s91, 0
	v_cmp_ne_u32_e32 vcc, 0, v48
	s_nop 1
	v_cndmask_b32_e32 v42, v8, v9, vcc
	v_cndmask_b32_e32 v43, v9, v8, vcc
; #define LAS __attribute__((address_space(3)))
; __device__ __forceinline__ bf16_t f2bf(float f) { return (bf16_t)(cvt_pk_bf16(f, 0.f) & 0xffffu); }
; __device__ __forceinline__ void dn_prep(const Params& p, LAS unsigned char* lds) {
;     ...
;             for (int i = 1; i < 64; ++i) {
; #pragma unroll
;                 for (int j4 = 8; j4 < (i + 3) / 4; ++j4) rhi[j4 - 8] = *(const LAS f32x4*)(Asz + i * 68 + j4 * 4);
;                 if (i + 1 < 64) {
; #pragma unroll
;                     for (int j4 = 0; j4 < ((i + 4) / 4 < 8 ? (i + 4) / 4 : 8); ++j4) rlo[(i + 1) & 1][j4] = *(const LAS f32x4*)(Asz + (i + 1) * 68 + j4 * 4);
;                 }
;                 float a0 = (lane == i) ? 1.f : 0.f, a1 = 0.f, a2 = 0.f, a3 = 0.f;
; #pragma unroll
;                 for (int j4 = 0; j4 < (i + 3) / 4; ++j4) {
;                     const f32x4 av = (j4 < 8) ? rlo[i & 1][j4 & 7] : rhi[(j4 - 8) & 7];
;                     if (j4 * 4 + 0 < i) a0 -= av[0] * T[j4 * 4 + 0];
;                     if (j4 * 4 + 1 < i) a1 -= av[1] * T[j4 * 4 + 1];
;                     if (j4 * 4 + 2 < i) a2 -= av[2] * T[j4 * 4 + 2];
;                     if (j4 * 4 + 3 < i) a3 -= av[3] * T[j4 * 4 + 3];
;                 }
;                 T[i] = (a0 + a1) + (a2 + a3);
;                 tub[i * 72] = f2bf(T[i] * bc); twb[i * 72] = f2bf(T[i] * wcf);
.Lfs_b2:
	s_cmp_gt_u32 s1, 2
	s_cbranch_scc1 .Lfs_z2
	s_waitcnt lgkmcnt(4)
	v_mul_f32_e32 v24, v72, v42
	v_mul_f32_e32 v25, v79, v42
	v_mul_f32_e32 v26, v86, v42
	v_mul_f32_e32 v27, v93, v42
	v_mul_f32_e32 v28, v100, v42
	v_mul_f32_e32 v29, v107, v42
	v_mul_f32_e32 v30, v114, v42
	v_mul_f32_e32 v31, v121, v42
	v_fmac_f32_dpp v24, v72, v43 row_ror:8 row_mask:0xf bank_mask:0xf
	v_fmac_f32_dpp v25, v79, v43 row_ror:8 row_mask:0xf bank_mask:0xf
	v_fmac_f32_dpp v26, v86, v43 row_ror:8 row_mask:0xf bank_mask:0xf
	v_fmac_f32_dpp v27, v93, v43 row_ror:8 row_mask:0xf bank_mask:0xf
	v_fmac_f32_dpp v28, v100, v43 row_ror:8 row_mask:0xf bank_mask:0xf
	v_fmac_f32_dpp v29, v107, v43 row_ror:8 row_mask:0xf bank_mask:0xf
	v_fmac_f32_dpp v30, v114, v43 row_ror:8 row_mask:0xf bank_mask:0xf
	v_fmac_f32_dpp v31, v121, v43 row_ror:8 row_mask:0xf bank_mask:0xf
	v_add_f32_dpp v24, v24, v24 quad_perm:[1,0,3,2] row_mask:0xf bank_mask:0xf bound_ctrl:1
	v_add_f32_dpp v25, v25, v25 quad_perm:[1,0,3,2] row_mask:0xf bank_mask:0xf bound_ctrl:1
	v_add_f32_dpp v26, v26, v26 quad_perm:[1,0,3,2] row_mask:0xf bank_mask:0xf bound_ctrl:1
	v_add_f32_dpp v27, v27, v27 quad_perm:[1,0,3,2] row_mask:0xf bank_mask:0xf bound_ctrl:1
	v_add_f32_dpp v28, v28, v28 quad_perm:[1,0,3,2] row_mask:0xf bank_mask:0xf bound_ctrl:1
	v_add_f32_dpp v29, v29, v29 quad_perm:[1,0,3,2] row_mask:0xf bank_mask:0xf bound_ctrl:1
	v_add_f32_dpp v30, v30, v30 quad_perm:[1,0,3,2] row_mask:0xf bank_mask:0xf bound_ctrl:1
	v_add_f32_dpp v31, v31, v31 quad_perm:[1,0,3,2] row_mask:0xf bank_mask:0xf bound_ctrl:1
	v_add_f32_dpp v24, v24, v24 quad_perm:[2,3,0,1] row_mask:0xf bank_mask:0xf bound_ctrl:1
	v_add_f32_dpp v25, v25, v25 quad_perm:[2,3,0,1] row_mask:0xf bank_mask:0xf bound_ctrl:1
	v_add_f32_dpp v26, v26, v26 quad_perm:[2,3,0,1] row_mask:0xf bank_mask:0xf bound_ctrl:1
	v_add_f32_dpp v27, v27, v27 quad_perm:[2,3,0,1] row_mask:0xf bank_mask:0xf bound_ctrl:1
	v_add_f32_dpp v28, v28, v28 quad_perm:[2,3,0,1] row_mask:0xf bank_mask:0xf bound_ctrl:1
	v_add_f32_dpp v29, v29, v29 quad_perm:[2,3,0,1] row_mask:0xf bank_mask:0xf bound_ctrl:1
	v_add_f32_dpp v30, v30, v30 quad_perm:[2,3,0,1] row_mask:0xf bank_mask:0xf bound_ctrl:1
	v_add_f32_dpp v31, v31, v31 quad_perm:[2,3,0,1] row_mask:0xf bank_mask:0xf bound_ctrl:1
	v_add_f32_dpp v24, v24, v24 row_half_mirror row_mask:0xf bank_mask:0xf bound_ctrl:1
	v_add_f32_dpp v25, v25, v25 row_half_mirror row_mask:0xf bank_mask:0xf bound_ctrl:1
	v_add_f32_dpp v26, v26, v26 row_half_mirror row_mask:0xf bank_mask:0xf bound_ctrl:1
	v_add_f32_dpp v27, v27, v27 row_half_mirror row_mask:0xf bank_mask:0xf bound_ctrl:1
	v_add_f32_dpp v28, v28, v28 row_half_mirror row_mask:0xf bank_mask:0xf bound_ctrl:1
	v_add_f32_dpp v29, v29, v29 row_half_mirror row_mask:0xf bank_mask:0xf bound_ctrl:1
	v_add_f32_dpp v30, v30, v30 row_half_mirror row_mask:0xf bank_mask:0xf bound_ctrl:1
	v_add_f32_dpp v31, v31, v31 row_half_mirror row_mask:0xf bank_mask:0xf bound_ctrl:1
	v_fma_f32 v24, v16, s91, -v24
	v_fma_f32 v25, v17, s91, -v25
	v_fma_f32 v26, v18, s91, -v26
	v_fma_f32 v27, v19, s91, -v27
	v_fma_f32 v28, v20, s91, -v28
	v_fma_f32 v29, v21, s91, -v29
	v_fma_f32 v30, v22, s91, -v30
	v_fma_f32 v31, v23, s91, -v31
	s_waitcnt lgkmcnt(0)
	ds_read_b32 v72, v49 offset:6528
	ds_read_b32 v74, v0 offset:6592
	ds_read_b32 v79, v49 offset:6800
	ds_read_b32 v81, v0 offset:6864
	ds_read_b32 v86, v49 offset:7072
	ds_read_b32 v88, v0 offset:7136
	ds_read_b32 v93, v49 offset:7344
	ds_read_b32 v95, v0 offset:7408
	ds_read_b32 v100, v49 offset:7616
	ds_read_b32 v102, v0 offset:7680
	ds_read_b32 v107, v49 offset:7888
	ds_read_b32 v109, v0 offset:7952
	ds_read_b32 v114, v49 offset:8160
	ds_read_b32 v116, v0 offset:8224
	ds_read_b32 v121, v49 offset:8432
	ds_read_b32 v123, v0 offset:8496
	v_mov_b32_e32 v10, v24
	v_cndmask_b32_e64 v10, v10, v25, s[6:7]
	v_cndmask_b32_e64 v10, v10, v26, s[68:69]
	v_cndmask_b32_e64 v10, v10, v27, s[92:93]
	v_cndmask_b32_e64 v10, v10, v28, s[94:95]
	v_cndmask_b32_e64 v10, v10, v29, s[96:97]
	v_cndmask_b32_e64 v10, v10, v30, s[98:99]
	v_cndmask_b32_e64 v10, v10, v31, s[100:101]
	s_nop 1
	v_mov_b32_dpp v41, v10 quad_perm:[0,0,0,0] row_mask:0xf bank_mask:0xf
	s_nop 1
	v_mov_b32_dpp v41, v41 row_half_mirror row_mask:0xf bank_mask:0xa
	v_fma_f32 v10, -v32, v41, v10
	s_nop 1
	v_mov_b32_dpp v41, v10 quad_perm:[1,1,1,1] row_mask:0xf bank_mask:0xf
	s_nop 1
	v_mov_b32_dpp v41, v41 row_half_mirror row_mask:0xf bank_mask:0xa
	v_fma_f32 v10, -v33, v41, v10
	s_nop 1
	v_mov_b32_dpp v41, v10 quad_perm:[2,2,2,2] row_mask:0xf bank_mask:0xf
	s_nop 1
	v_mov_b32_dpp v41, v41 row_half_mirror row_mask:0xf bank_mask:0xa
	v_fma_f32 v10, -v34, v41, v10
	s_nop 1
	v_mov_b32_dpp v41, v10 quad_perm:[3,3,3,3] row_mask:0xf bank_mask:0xf
	s_nop 1
	v_mov_b32_dpp v41, v41 row_half_mirror row_mask:0xf bank_mask:0xa
	v_fma_f32 v10, -v35, v41, v10
	s_nop 1
	v_mov_b32_dpp v41, v10 quad_perm:[0,0,0,0] row_mask:0xf bank_mask:0xf
	v_fma_f32 v10, -v36, v41, v10
	s_nop 1
	v_mov_b32_dpp v41, v10 quad_perm:[1,1,1,1] row_mask:0xf bank_mask:0xf
	v_fma_f32 v10, -v37, v41, v10
	s_nop 1
	v_mov_b32_dpp v41, v10 quad_perm:[2,2,2,2] row_mask:0xf bank_mask:0xf
	v_fma_f32 v10, -v38, v41, v10
	ds_read_b128 v[32:35], v40 offset:6624
	ds_read_b128 v[36:39], v40 offset:6640
	v_mul_f32_e32 v128, v4, v10
	v_mul_f32_e32 v129, v5, v10
	v_cvt_pk_bf16_f32 v128, v128, v128
	v_cvt_pk_bf16_f32 v129, v129, v129
	ds_write_b16 v2, v128 offset:2304
	ds_write_b16 v3, v129 offset:2304
	s_mov_b32 s91, 0
; #define LAS __attribute__((address_space(3)))
; __device__ __forceinline__ bf16_t f2bf(float f) { return (bf16_t)(cvt_pk_bf16(f, 0.f) & 0xffffu); }
; __device__ __forceinline__ void dn_prep(const Params& p, LAS unsigned char* lds) {
;     ...
;             for (int i = 1; i < 64; ++i) {
; #pragma unroll
;                 for (int j4 = 8; j4 < (i + 3) / 4; ++j4) rhi[j4 - 8] = *(const LAS f32x4*)(Asz + i * 68 + j4 * 4);
;                 if (i + 1 < 64) {
; #pragma unroll
;                     for (int j4 = 0; j4 < ((i + 4) / 4 < 8 ? (i + 4) / 4 : 8); ++j4) rlo[(i + 1) & 1][j4] = *(const LAS f32x4*)(Asz + (i + 1) * 68 + j4 * 4);
;                 }
;                 float a0 = (lane == i) ? 1.f : 0.f, a1 = 0.f, a2 = 0.f, a3 = 0.f;
; #pragma unroll
;                 for (int j4 = 0; j4 < (i + 3) / 4; ++j4) {
;                     const f32x4 av = (j4 < 8) ? rlo[i & 1][j4 & 7] : rhi[(j4 - 8) & 7];
;                     if (j4 * 4 + 0 < i) a0 -= av[0] * T[j4 * 4 + 0];
;                     if (j4 * 4 + 1 < i) a1 -= av[1] * T[j4 * 4 + 1];
;                     if (j4 * 4 + 2 < i) a2 -= av[2] * T[j4 * 4 + 2];
;                     if (j4 * 4 + 3 < i) a3 -= av[3] * T[j4 * 4 + 3];
;                 }
;                 T[i] = (a0 + a1) + (a2 + a3);
;                 tub[i * 72] = f2bf(T[i] * bc); twb[i * 72] = f2bf(T[i] * wcf);
.Lfs_b3:
	s_cmp_gt_u32 s1, 3
	s_cbranch_scc1 .Lfs_z3
	s_waitcnt lgkmcnt(4)
	v_mul_f32_e32 v24, v72, v42
	v_mul_f32_e32 v25, v79, v42
	v_mul_f32_e32 v26, v86, v42
	v_mul_f32_e32 v27, v93, v42
	v_mul_f32_e32 v28, v100, v42
	v_mul_f32_e32 v29, v107, v42
	v_mul_f32_e32 v30, v114, v42
	v_mul_f32_e32 v31, v121, v42
	v_fmac_f32_dpp v24, v72, v43 row_ror:8 row_mask:0xf bank_mask:0xf
	v_fmac_f32_dpp v25, v79, v43 row_ror:8 row_mask:0xf bank_mask:0xf
	v_fmac_f32_dpp v26, v86, v43 row_ror:8 row_mask:0xf bank_mask:0xf
	v_fmac_f32_dpp v27, v93, v43 row_ror:8 row_mask:0xf bank_mask:0xf
	v_fmac_f32_dpp v28, v100, v43 row_ror:8 row_mask:0xf bank_mask:0xf
	v_fmac_f32_dpp v29, v107, v43 row_ror:8 row_mask:0xf bank_mask:0xf
	v_fmac_f32_dpp v30, v114, v43 row_ror:8 row_mask:0xf bank_mask:0xf
	v_fmac_f32_dpp v31, v121, v43 row_ror:8 row_mask:0xf bank_mask:0xf
	v_fmac_f32_e32 v24, v74, v10
	v_fmac_f32_e32 v25, v81, v10
	v_fmac_f32_e32 v26, v88, v10
	v_fmac_f32_e32 v27, v95, v10
	v_fmac_f32_e32 v28, v102, v10
	v_fmac_f32_e32 v29, v109, v10
	v_fmac_f32_e32 v30, v116, v10
	v_fmac_f32_e32 v31, v123, v10
	v_add_f32_dpp v24, v24, v24 quad_perm:[1,0,3,2] row_mask:0xf bank_mask:0xf bound_ctrl:1
	v_add_f32_dpp v25, v25, v25 quad_perm:[1,0,3,2] row_mask:0xf bank_mask:0xf bound_ctrl:1
	v_add_f32_dpp v26, v26, v26 quad_perm:[1,0,3,2] row_mask:0xf bank_mask:0xf bound_ctrl:1
	v_add_f32_dpp v27, v27, v27 quad_perm:[1,0,3,2] row_mask:0xf bank_mask:0xf bound_ctrl:1
	v_add_f32_dpp v28, v28, v28 quad_perm:[1,0,3,2] row_mask:0xf bank_mask:0xf bound_ctrl:1
	v_add_f32_dpp v29, v29, v29 quad_perm:[1,0,3,2] row_mask:0xf bank_mask:0xf bound_ctrl:1
	v_add_f32_dpp v30, v30, v30 quad_perm:[1,0,3,2] row_mask:0xf bank_mask:0xf bound_ctrl:1
	v_add_f32_dpp v31, v31, v31 quad_perm:[1,0,3,2] row_mask:0xf bank_mask:0xf bound_ctrl:1
	v_add_f32_dpp v24, v24, v24 quad_perm:[2,3,0,1] row_mask:0xf bank_mask:0xf bound_ctrl:1
	v_add_f32_dpp v25, v25, v25 quad_perm:[2,3,0,1] row_mask:0xf bank_mask:0xf bound_ctrl:1
	v_add_f32_dpp v26, v26, v26 quad_perm:[2,3,0,1] row_mask:0xf bank_mask:0xf bound_ctrl:1
	v_add_f32_dpp v27, v27, v27 quad_perm:[2,3,0,1] row_mask:0xf bank_mask:0xf bound_ctrl:1
	v_add_f32_dpp v28, v28, v28 quad_perm:[2,3,0,1] row_mask:0xf bank_mask:0xf bound_ctrl:1
	v_add_f32_dpp v29, v29, v29 quad_perm:[2,3,0,1] row_mask:0xf bank_mask:0xf bound_ctrl:1
	v_add_f32_dpp v30, v30, v30 quad_perm:[2,3,0,1] row_mask:0xf bank_mask:0xf bound_ctrl:1
	v_add_f32_dpp v31, v31, v31 quad_perm:[2,3,0,1] row_mask:0xf bank_mask:0xf bound_ctrl:1
	v_add_f32_dpp v24, v24, v24 row_half_mirror row_mask:0xf bank_mask:0xf bound_ctrl:1
	v_add_f32_dpp v25, v25, v25 row_half_mirror row_mask:0xf bank_mask:0xf bound_ctrl:1
	v_add_f32_dpp v26, v26, v26 row_half_mirror row_mask:0xf bank_mask:0xf bound_ctrl:1
	v_add_f32_dpp v27, v27, v27 row_half_mirror row_mask:0xf bank_mask:0xf bound_ctrl:1
	v_add_f32_dpp v28, v28, v28 row_half_mirror row_mask:0xf bank_mask:0xf bound_ctrl:1
	v_add_f32_dpp v29, v29, v29 row_half_mirror row_mask:0xf bank_mask:0xf bound_ctrl:1
	v_add_f32_dpp v30, v30, v30 row_half_mirror row_mask:0xf bank_mask:0xf bound_ctrl:1
	v_add_f32_dpp v31, v31, v31 row_half_mirror row_mask:0xf bank_mask:0xf bound_ctrl:1
	v_fma_f32 v24, v16, s91, -v24
	v_fma_f32 v25, v17, s91, -v25
	v_fma_f32 v26, v18, s91, -v26
	v_fma_f32 v27, v19, s91, -v27
	v_fma_f32 v28, v20, s91, -v28
	v_fma_f32 v29, v21, s91, -v29
	v_fma_f32 v30, v22, s91, -v30
	v_fma_f32 v31, v23, s91, -v31
	s_waitcnt lgkmcnt(0)
	ds_read_b32 v72, v49 offset:8704
	ds_read_b32 v74, v49 offset:8768
	ds_read_b32 v79, v49 offset:8976
	ds_read_b32 v81, v49 offset:9040
	ds_read_b32 v86, v49 offset:9248
	ds_read_b32 v88, v49 offset:9312
	ds_read_b32 v93, v49 offset:9520
	ds_read_b32 v95, v49 offset:9584
	ds_read_b32 v100, v49 offset:9792
	ds_read_b32 v102, v49 offset:9856
	ds_read_b32 v107, v49 offset:10064
	ds_read_b32 v109, v49 offset:10128
	ds_read_b32 v114, v49 offset:10336
	ds_read_b32 v116, v49 offset:10400
	ds_read_b32 v121, v49 offset:10608
	ds_read_b32 v123, v49 offset:10672
	v_mov_b32_e32 v11, v24
	v_cndmask_b32_e64 v11, v11, v25, s[6:7]
	v_cndmask_b32_e64 v11, v11, v26, s[68:69]
	v_cndmask_b32_e64 v11, v11, v27, s[92:93]
	v_cndmask_b32_e64 v11, v11, v28, s[94:95]
	v_cndmask_b32_e64 v11, v11, v29, s[96:97]
	v_cndmask_b32_e64 v11, v11, v30, s[98:99]
	v_cndmask_b32_e64 v11, v11, v31, s[100:101]
	s_nop 1
	v_mov_b32_dpp v41, v11 quad_perm:[0,0,0,0] row_mask:0xf bank_mask:0xf
	s_nop 1
	v_mov_b32_dpp v41, v41 row_half_mirror row_mask:0xf bank_mask:0xa
	v_fma_f32 v11, -v32, v41, v11
	s_nop 1
	v_mov_b32_dpp v41, v11 quad_perm:[1,1,1,1] row_mask:0xf bank_mask:0xf
	s_nop 1
	v_mov_b32_dpp v41, v41 row_half_mirror row_mask:0xf bank_mask:0xa
	v_fma_f32 v11, -v33, v41, v11
	s_nop 1
	v_mov_b32_dpp v41, v11 quad_perm:[2,2,2,2] row_mask:0xf bank_mask:0xf
	s_nop 1
	v_mov_b32_dpp v41, v41 row_half_mirror row_mask:0xf bank_mask:0xa
	v_fma_f32 v11, -v34, v41, v11
	s_nop 1
	v_mov_b32_dpp v41, v11 quad_perm:[3,3,3,3] row_mask:0xf bank_mask:0xf
	s_nop 1
	v_mov_b32_dpp v41, v41 row_half_mirror row_mask:0xf bank_mask:0xa
	v_fma_f32 v11, -v35, v41, v11
	s_nop 1
	v_mov_b32_dpp v41, v11 quad_perm:[0,0,0,0] row_mask:0xf bank_mask:0xf
	v_fma_f32 v11, -v36, v41, v11
	s_nop 1
	v_mov_b32_dpp v41, v11 quad_perm:[1,1,1,1] row_mask:0xf bank_mask:0xf
	v_fma_f32 v11, -v37, v41, v11
	s_nop 1
	v_mov_b32_dpp v41, v11 quad_perm:[2,2,2,2] row_mask:0xf bank_mask:0xf
	v_fma_f32 v11, -v38, v41, v11
	ds_read_b128 v[32:35], v40 offset:8832
	ds_read_b128 v[36:39], v40 offset:8848
	v_mul_f32_e32 v128, v4, v11
	v_mul_f32_e32 v129, v5, v11
	v_cvt_pk_bf16_f32 v128, v128, v128
	v_cvt_pk_bf16_f32 v129, v129, v129
	ds_write_b16 v2, v128 offset:3456
	ds_write_b16 v3, v129 offset:3456
	s_mov_b32 s91, 0
	v_cmp_ne_u32_e32 vcc, 0, v48
	s_nop 1
	v_cndmask_b32_e32 v44, v10, v11, vcc
	v_cndmask_b32_e32 v45, v11, v10, vcc
; #define LAS __attribute__((address_space(3)))
; __device__ __forceinline__ bf16_t f2bf(float f) { return (bf16_t)(cvt_pk_bf16(f, 0.f) & 0xffffu); }
; __device__ __forceinline__ void dn_prep(const Params& p, LAS unsigned char* lds) {
;     ...
;             for (int i = 1; i < 64; ++i) {
; #pragma unroll
;                 for (int j4 = 8; j4 < (i + 3) / 4; ++j4) rhi[j4 - 8] = *(const LAS f32x4*)(Asz + i * 68 + j4 * 4);
;                 if (i + 1 < 64) {
; #pragma unroll
;                     for (int j4 = 0; j4 < ((i + 4) / 4 < 8 ? (i + 4) / 4 : 8); ++j4) rlo[(i + 1) & 1][j4] = *(const LAS f32x4*)(Asz + (i + 1) * 68 + j4 * 4);
;                 }
;                 float a0 = (lane == i) ? 1.f : 0.f, a1 = 0.f, a2 = 0.f, a3 = 0.f;
; #pragma unroll
;                 for (int j4 = 0; j4 < (i + 3) / 4; ++j4) {
;                     const f32x4 av = (j4 < 8) ? rlo[i & 1][j4 & 7] : rhi[(j4 - 8) & 7];
;                     if (j4 * 4 + 0 < i) a0 -= av[0] * T[j4 * 4 + 0];
;                     if (j4 * 4 + 1 < i) a1 -= av[1] * T[j4 * 4 + 1];
;                     if (j4 * 4 + 2 < i) a2 -= av[2] * T[j4 * 4 + 2];
;                     if (j4 * 4 + 3 < i) a3 -= av[3] * T[j4 * 4 + 3];
;                 }
;                 T[i] = (a0 + a1) + (a2 + a3);
;                 tub[i * 72] = f2bf(T[i] * bc); twb[i * 72] = f2bf(T[i] * wcf);
.Lfs_b4:
	s_cmp_gt_u32 s1, 4
	s_cbranch_scc1 .Lfs_z4
	s_waitcnt lgkmcnt(4)
	v_mul_f32_e32 v24, v72, v42
	v_mul_f32_e32 v25, v79, v42
	v_mul_f32_e32 v26, v86, v42
	v_mul_f32_e32 v27, v93, v42
	v_mul_f32_e32 v28, v100, v42
	v_mul_f32_e32 v29, v107, v42
	v_mul_f32_e32 v30, v114, v42
	v_mul_f32_e32 v31, v121, v42
	v_fmac_f32_dpp v24, v72, v43 row_ror:8 row_mask:0xf bank_mask:0xf
	v_fmac_f32_dpp v25, v79, v43 row_ror:8 row_mask:0xf bank_mask:0xf
	v_fmac_f32_dpp v26, v86, v43 row_ror:8 row_mask:0xf bank_mask:0xf
	v_fmac_f32_dpp v27, v93, v43 row_ror:8 row_mask:0xf bank_mask:0xf
	v_fmac_f32_dpp v28, v100, v43 row_ror:8 row_mask:0xf bank_mask:0xf
	v_fmac_f32_dpp v29, v107, v43 row_ror:8 row_mask:0xf bank_mask:0xf
	v_fmac_f32_dpp v30, v114, v43 row_ror:8 row_mask:0xf bank_mask:0xf
	v_fmac_f32_dpp v31, v121, v43 row_ror:8 row_mask:0xf bank_mask:0xf
	v_fmac_f32_e32 v24, v74, v44
	v_fmac_f32_e32 v25, v81, v44
	v_fmac_f32_e32 v26, v88, v44
	v_fmac_f32_e32 v27, v95, v44
	v_fmac_f32_e32 v28, v102, v44
	v_fmac_f32_e32 v29, v109, v44
	v_fmac_f32_e32 v30, v116, v44
	v_fmac_f32_e32 v31, v123, v44
	v_fmac_f32_dpp v24, v74, v45 row_ror:8 row_mask:0xf bank_mask:0xf
	v_fmac_f32_dpp v25, v81, v45 row_ror:8 row_mask:0xf bank_mask:0xf
	v_fmac_f32_dpp v26, v88, v45 row_ror:8 row_mask:0xf bank_mask:0xf
	v_fmac_f32_dpp v27, v95, v45 row_ror:8 row_mask:0xf bank_mask:0xf
	v_fmac_f32_dpp v28, v102, v45 row_ror:8 row_mask:0xf bank_mask:0xf
	v_fmac_f32_dpp v29, v109, v45 row_ror:8 row_mask:0xf bank_mask:0xf
	v_fmac_f32_dpp v30, v116, v45 row_ror:8 row_mask:0xf bank_mask:0xf
	v_fmac_f32_dpp v31, v123, v45 row_ror:8 row_mask:0xf bank_mask:0xf
	v_add_f32_dpp v24, v24, v24 quad_perm:[1,0,3,2] row_mask:0xf bank_mask:0xf bound_ctrl:1
	v_add_f32_dpp v25, v25, v25 quad_perm:[1,0,3,2] row_mask:0xf bank_mask:0xf bound_ctrl:1
	v_add_f32_dpp v26, v26, v26 quad_perm:[1,0,3,2] row_mask:0xf bank_mask:0xf bound_ctrl:1
	v_add_f32_dpp v27, v27, v27 quad_perm:[1,0,3,2] row_mask:0xf bank_mask:0xf bound_ctrl:1
	v_add_f32_dpp v28, v28, v28 quad_perm:[1,0,3,2] row_mask:0xf bank_mask:0xf bound_ctrl:1
	v_add_f32_dpp v29, v29, v29 quad_perm:[1,0,3,2] row_mask:0xf bank_mask:0xf bound_ctrl:1
	v_add_f32_dpp v30, v30, v30 quad_perm:[1,0,3,2] row_mask:0xf bank_mask:0xf bound_ctrl:1
	v_add_f32_dpp v31, v31, v31 quad_perm:[1,0,3,2] row_mask:0xf bank_mask:0xf bound_ctrl:1
	v_add_f32_dpp v24, v24, v24 quad_perm:[2,3,0,1] row_mask:0xf bank_mask:0xf bound_ctrl:1
	v_add_f32_dpp v25, v25, v25 quad_perm:[2,3,0,1] row_mask:0xf bank_mask:0xf bound_ctrl:1
	v_add_f32_dpp v26, v26, v26 quad_perm:[2,3,0,1] row_mask:0xf bank_mask:0xf bound_ctrl:1
	v_add_f32_dpp v27, v27, v27 quad_perm:[2,3,0,1] row_mask:0xf bank_mask:0xf bound_ctrl:1
	v_add_f32_dpp v28, v28, v28 quad_perm:[2,3,0,1] row_mask:0xf bank_mask:0xf bound_ctrl:1
	v_add_f32_dpp v29, v29, v29 quad_perm:[2,3,0,1] row_mask:0xf bank_mask:0xf bound_ctrl:1
	v_add_f32_dpp v30, v30, v30 quad_perm:[2,3,0,1] row_mask:0xf bank_mask:0xf bound_ctrl:1
	v_add_f32_dpp v31, v31, v31 quad_perm:[2,3,0,1] row_mask:0xf bank_mask:0xf bound_ctrl:1
	v_add_f32_dpp v24, v24, v24 row_half_mirror row_mask:0xf bank_mask:0xf bound_ctrl:1
	v_add_f32_dpp v25, v25, v25 row_half_mirror row_mask:0xf bank_mask:0xf bound_ctrl:1
	v_add_f32_dpp v26, v26, v26 row_half_mirror row_mask:0xf bank_mask:0xf bound_ctrl:1
	v_add_f32_dpp v27, v27, v27 row_half_mirror row_mask:0xf bank_mask:0xf bound_ctrl:1
	v_add_f32_dpp v28, v28, v28 row_half_mirror row_mask:0xf bank_mask:0xf bound_ctrl:1
	v_add_f32_dpp v29, v29, v29 row_half_mirror row_mask:0xf bank_mask:0xf bound_ctrl:1
	v_add_f32_dpp v30, v30, v30 row_half_mirror row_mask:0xf bank_mask:0xf bound_ctrl:1
	v_add_f32_dpp v31, v31, v31 row_half_mirror row_mask:0xf bank_mask:0xf bound_ctrl:1
	v_fma_f32 v24, v16, s91, -v24
	v_fma_f32 v25, v17, s91, -v25
	v_fma_f32 v26, v18, s91, -v26
	v_fma_f32 v27, v19, s91, -v27
	v_fma_f32 v28, v20, s91, -v28
	v_fma_f32 v29, v21, s91, -v29
	v_fma_f32 v30, v22, s91, -v30
	v_fma_f32 v31, v23, s91, -v31
	s_waitcnt lgkmcnt(0)
	ds_read_b32 v72, v49 offset:10880
	ds_read_b32 v74, v49 offset:10944
	ds_read_b32 v76, v0 offset:11008
	ds_read_b32 v79, v49 offset:11152
	ds_read_b32 v81, v49 offset:11216
	ds_read_b32 v83, v0 offset:11280
	ds_read_b32 v86, v49 offset:11424
	ds_read_b32 v88, v49 offset:11488
	ds_read_b32 v90, v0 offset:11552
	ds_read_b32 v93, v49 offset:11696
	ds_read_b32 v95, v49 offset:11760
	ds_read_b32 v97, v0 offset:11824
	ds_read_b32 v100, v49 offset:11968
	ds_read_b32 v102, v49 offset:12032
	ds_read_b32 v104, v0 offset:12096
	ds_read_b32 v107, v49 offset:12240
	ds_read_b32 v109, v49 offset:12304
	ds_read_b32 v111, v0 offset:12368
	ds_read_b32 v114, v49 offset:12512
	ds_read_b32 v116, v49 offset:12576
	ds_read_b32 v118, v0 offset:12640
	ds_read_b32 v121, v49 offset:12784
	ds_read_b32 v123, v49 offset:12848
	ds_read_b32 v125, v0 offset:12912
	v_mov_b32_e32 v12, v24
	v_cndmask_b32_e64 v12, v12, v25, s[6:7]
	v_cndmask_b32_e64 v12, v12, v26, s[68:69]
	v_cndmask_b32_e64 v12, v12, v27, s[92:93]
	v_cndmask_b32_e64 v12, v12, v28, s[94:95]
	v_cndmask_b32_e64 v12, v12, v29, s[96:97]
	v_cndmask_b32_e64 v12, v12, v30, s[98:99]
	v_cndmask_b32_e64 v12, v12, v31, s[100:101]
	s_nop 1
	v_mov_b32_dpp v41, v12 quad_perm:[0,0,0,0] row_mask:0xf bank_mask:0xf
	s_nop 1
	v_mov_b32_dpp v41, v41 row_half_mirror row_mask:0xf bank_mask:0xa
	v_fma_f32 v12, -v32, v41, v12
	s_nop 1
	v_mov_b32_dpp v41, v12 quad_perm:[1,1,1,1] row_mask:0xf bank_mask:0xf
	s_nop 1
	v_mov_b32_dpp v41, v41 row_half_mirror row_mask:0xf bank_mask:0xa
	v_fma_f32 v12, -v33, v41, v12
	s_nop 1
	v_mov_b32_dpp v41, v12 quad_perm:[2,2,2,2] row_mask:0xf bank_mask:0xf
	s_nop 1
	v_mov_b32_dpp v41, v41 row_half_mirror row_mask:0xf bank_mask:0xa
	v_fma_f32 v12, -v34, v41, v12
	s_nop 1
	v_mov_b32_dpp v41, v12 quad_perm:[3,3,3,3] row_mask:0xf bank_mask:0xf
	s_nop 1
	v_mov_b32_dpp v41, v41 row_half_mirror row_mask:0xf bank_mask:0xa
	v_fma_f32 v12, -v35, v41, v12
	s_nop 1
	v_mov_b32_dpp v41, v12 quad_perm:[0,0,0,0] row_mask:0xf bank_mask:0xf
	v_fma_f32 v12, -v36, v41, v12
	s_nop 1
	v_mov_b32_dpp v41, v12 quad_perm:[1,1,1,1] row_mask:0xf bank_mask:0xf
	v_fma_f32 v12, -v37, v41, v12
	s_nop 1
	v_mov_b32_dpp v41, v12 quad_perm:[2,2,2,2] row_mask:0xf bank_mask:0xf
	v_fma_f32 v12, -v38, v41, v12
	ds_read_b128 v[32:35], v40 offset:11040
	ds_read_b128 v[36:39], v40 offset:11056
	v_mul_f32_e32 v128, v4, v12
	v_mul_f32_e32 v129, v5, v12
	v_cvt_pk_bf16_f32 v128, v128, v128
	v_cvt_pk_bf16_f32 v129, v129, v129
	ds_write_b16 v2, v128 offset:4608
	ds_write_b16 v3, v129 offset:4608
	s_mov_b32 s91, 0
; #define LAS __attribute__((address_space(3)))
; __device__ __forceinline__ bf16_t f2bf(float f) { return (bf16_t)(cvt_pk_bf16(f, 0.f) & 0xffffu); }
; __device__ __forceinline__ void dn_prep(const Params& p, LAS unsigned char* lds) {
;     ...
;             for (int i = 1; i < 64; ++i) {
; #pragma unroll
;                 for (int j4 = 8; j4 < (i + 3) / 4; ++j4) rhi[j4 - 8] = *(const LAS f32x4*)(Asz + i * 68 + j4 * 4);
;                 if (i + 1 < 64) {
; #pragma unroll
;                     for (int j4 = 0; j4 < ((i + 4) / 4 < 8 ? (i + 4) / 4 : 8); ++j4) rlo[(i + 1) & 1][j4] = *(const LAS f32x4*)(Asz + (i + 1) * 68 + j4 * 4);
;                 }
;                 float a0 = (lane == i) ? 1.f : 0.f, a1 = 0.f, a2 = 0.f, a3 = 0.f;
; #pragma unroll
;                 for (int j4 = 0; j4 < (i + 3) / 4; ++j4) {
;                     const f32x4 av = (j4 < 8) ? rlo[i & 1][j4 & 7] : rhi[(j4 - 8) & 7];
;                     if (j4 * 4 + 0 < i) a0 -= av[0] * T[j4 * 4 + 0];
;                     if (j4 * 4 + 1 < i) a1 -= av[1] * T[j4 * 4 + 1];
;                     if (j4 * 4 + 2 < i) a2 -= av[2] * T[j4 * 4 + 2];
;                     if (j4 * 4 + 3 < i) a3 -= av[3] * T[j4 * 4 + 3];
;                 }
;                 T[i] = (a0 + a1) + (a2 + a3);
;                 tub[i * 72] = f2bf(T[i] * bc); twb[i * 72] = f2bf(T[i] * wcf);
.Lfs_b5:
	s_cmp_gt_u32 s1, 5
	s_cbranch_scc1 .Lfs_z5
	s_waitcnt lgkmcnt(4)
	v_mul_f32_e32 v24, v72, v42
	v_mul_f32_e32 v25, v79, v42
	v_mul_f32_e32 v26, v86, v42
	v_mul_f32_e32 v27, v93, v42
	v_mul_f32_e32 v28, v100, v42
	v_mul_f32_e32 v29, v107, v42
	v_mul_f32_e32 v30, v114, v42
	v_mul_f32_e32 v31, v121, v42
	v_fmac_f32_dpp v24, v72, v43 row_ror:8 row_mask:0xf bank_mask:0xf
	v_fmac_f32_dpp v25, v79, v43 row_ror:8 row_mask:0xf bank_mask:0xf
	v_fmac_f32_dpp v26, v86, v43 row_ror:8 row_mask:0xf bank_mask:0xf
	v_fmac_f32_dpp v27, v93, v43 row_ror:8 row_mask:0xf bank_mask:0xf
	v_fmac_f32_dpp v28, v100, v43 row_ror:8 row_mask:0xf bank_mask:0xf
	v_fmac_f32_dpp v29, v107, v43 row_ror:8 row_mask:0xf bank_mask:0xf
	v_fmac_f32_dpp v30, v114, v43 row_ror:8 row_mask:0xf bank_mask:0xf
	v_fmac_f32_dpp v31, v121, v43 row_ror:8 row_mask:0xf bank_mask:0xf
	v_fmac_f32_e32 v24, v74, v44
	v_fmac_f32_e32 v25, v81, v44
	v_fmac_f32_e32 v26, v88, v44
	v_fmac_f32_e32 v27, v95, v44
	v_fmac_f32_e32 v28, v102, v44
	v_fmac_f32_e32 v29, v109, v44
	v_fmac_f32_e32 v30, v116, v44
	v_fmac_f32_e32 v31, v123, v44
	v_fmac_f32_dpp v24, v74, v45 row_ror:8 row_mask:0xf bank_mask:0xf
	v_fmac_f32_dpp v25, v81, v45 row_ror:8 row_mask:0xf bank_mask:0xf
	v_fmac_f32_dpp v26, v88, v45 row_ror:8 row_mask:0xf bank_mask:0xf
	v_fmac_f32_dpp v27, v95, v45 row_ror:8 row_mask:0xf bank_mask:0xf
	v_fmac_f32_dpp v28, v102, v45 row_ror:8 row_mask:0xf bank_mask:0xf
	v_fmac_f32_dpp v29, v109, v45 row_ror:8 row_mask:0xf bank_mask:0xf
	v_fmac_f32_dpp v30, v116, v45 row_ror:8 row_mask:0xf bank_mask:0xf
	v_fmac_f32_dpp v31, v123, v45 row_ror:8 row_mask:0xf bank_mask:0xf
	v_fmac_f32_e32 v24, v76, v12
	v_fmac_f32_e32 v25, v83, v12
	v_fmac_f32_e32 v26, v90, v12
	v_fmac_f32_e32 v27, v97, v12
	v_fmac_f32_e32 v28, v104, v12
	v_fmac_f32_e32 v29, v111, v12
	v_fmac_f32_e32 v30, v118, v12
	v_fmac_f32_e32 v31, v125, v12
	v_add_f32_dpp v24, v24, v24 quad_perm:[1,0,3,2] row_mask:0xf bank_mask:0xf bound_ctrl:1
	v_add_f32_dpp v25, v25, v25 quad_perm:[1,0,3,2] row_mask:0xf bank_mask:0xf bound_ctrl:1
	v_add_f32_dpp v26, v26, v26 quad_perm:[1,0,3,2] row_mask:0xf bank_mask:0xf bound_ctrl:1
	v_add_f32_dpp v27, v27, v27 quad_perm:[1,0,3,2] row_mask:0xf bank_mask:0xf bound_ctrl:1
	v_add_f32_dpp v28, v28, v28 quad_perm:[1,0,3,2] row_mask:0xf bank_mask:0xf bound_ctrl:1
	v_add_f32_dpp v29, v29, v29 quad_perm:[1,0,3,2] row_mask:0xf bank_mask:0xf bound_ctrl:1
	v_add_f32_dpp v30, v30, v30 quad_perm:[1,0,3,2] row_mask:0xf bank_mask:0xf bound_ctrl:1
	v_add_f32_dpp v31, v31, v31 quad_perm:[1,0,3,2] row_mask:0xf bank_mask:0xf bound_ctrl:1
	v_add_f32_dpp v24, v24, v24 quad_perm:[2,3,0,1] row_mask:0xf bank_mask:0xf bound_ctrl:1
	v_add_f32_dpp v25, v25, v25 quad_perm:[2,3,0,1] row_mask:0xf bank_mask:0xf bound_ctrl:1
	v_add_f32_dpp v26, v26, v26 quad_perm:[2,3,0,1] row_mask:0xf bank_mask:0xf bound_ctrl:1
	v_add_f32_dpp v27, v27, v27 quad_perm:[2,3,0,1] row_mask:0xf bank_mask:0xf bound_ctrl:1
	v_add_f32_dpp v28, v28, v28 quad_perm:[2,3,0,1] row_mask:0xf bank_mask:0xf bound_ctrl:1
	v_add_f32_dpp v29, v29, v29 quad_perm:[2,3,0,1] row_mask:0xf bank_mask:0xf bound_ctrl:1
	v_add_f32_dpp v30, v30, v30 quad_perm:[2,3,0,1] row_mask:0xf bank_mask:0xf bound_ctrl:1
	v_add_f32_dpp v31, v31, v31 quad_perm:[2,3,0,1] row_mask:0xf bank_mask:0xf bound_ctrl:1
	v_add_f32_dpp v24, v24, v24 row_half_mirror row_mask:0xf bank_mask:0xf bound_ctrl:1
	v_add_f32_dpp v25, v25, v25 row_half_mirror row_mask:0xf bank_mask:0xf bound_ctrl:1
	v_add_f32_dpp v26, v26, v26 row_half_mirror row_mask:0xf bank_mask:0xf bound_ctrl:1
	v_add_f32_dpp v27, v27, v27 row_half_mirror row_mask:0xf bank_mask:0xf bound_ctrl:1
	v_add_f32_dpp v28, v28, v28 row_half_mirror row_mask:0xf bank_mask:0xf bound_ctrl:1
	v_add_f32_dpp v29, v29, v29 row_half_mirror row_mask:0xf bank_mask:0xf bound_ctrl:1
	v_add_f32_dpp v30, v30, v30 row_half_mirror row_mask:0xf bank_mask:0xf bound_ctrl:1
	v_add_f32_dpp v31, v31, v31 row_half_mirror row_mask:0xf bank_mask:0xf bound_ctrl:1
	v_fma_f32 v24, v16, s91, -v24
	v_fma_f32 v25, v17, s91, -v25
	v_fma_f32 v26, v18, s91, -v26
	v_fma_f32 v27, v19, s91, -v27
	v_fma_f32 v28, v20, s91, -v28
	v_fma_f32 v29, v21, s91, -v29
	v_fma_f32 v30, v22, s91, -v30
	v_fma_f32 v31, v23, s91, -v31
	s_waitcnt lgkmcnt(0)
	ds_read_b32 v72, v49 offset:13056
	ds_read_b32 v74, v49 offset:13120
	ds_read_b32 v76, v49 offset:13184
	ds_read_b32 v79, v49 offset:13328
	ds_read_b32 v81, v49 offset:13392
	ds_read_b32 v83, v49 offset:13456
	ds_read_b32 v86, v49 offset:13600
	ds_read_b32 v88, v49 offset:13664
	ds_read_b32 v90, v49 offset:13728
	ds_read_b32 v93, v49 offset:13872
	ds_read_b32 v95, v49 offset:13936
	ds_read_b32 v97, v49 offset:14000
	ds_read_b32 v100, v49 offset:14144
	ds_read_b32 v102, v49 offset:14208
	ds_read_b32 v104, v49 offset:14272
	ds_read_b32 v107, v49 offset:14416
	ds_read_b32 v109, v49 offset:14480
	ds_read_b32 v111, v49 offset:14544
	ds_read_b32 v114, v49 offset:14688
	ds_read_b32 v116, v49 offset:14752
	ds_read_b32 v118, v49 offset:14816
	ds_read_b32 v121, v49 offset:14960
	ds_read_b32 v123, v49 offset:15024
	ds_read_b32 v125, v49 offset:15088
	v_mov_b32_e32 v13, v24
	v_cndmask_b32_e64 v13, v13, v25, s[6:7]
	v_cndmask_b32_e64 v13, v13, v26, s[68:69]
	v_cndmask_b32_e64 v13, v13, v27, s[92:93]
	v_cndmask_b32_e64 v13, v13, v28, s[94:95]
	v_cndmask_b32_e64 v13, v13, v29, s[96:97]
	v_cndmask_b32_e64 v13, v13, v30, s[98:99]
	v_cndmask_b32_e64 v13, v13, v31, s[100:101]
	s_nop 1
	v_mov_b32_dpp v41, v13 quad_perm:[0,0,0,0] row_mask:0xf bank_mask:0xf
	s_nop 1
	v_mov_b32_dpp v41, v41 row_half_mirror row_mask:0xf bank_mask:0xa
	v_fma_f32 v13, -v32, v41, v13
	s_nop 1
	v_mov_b32_dpp v41, v13 quad_perm:[1,1,1,1] row_mask:0xf bank_mask:0xf
	s_nop 1
	v_mov_b32_dpp v41, v41 row_half_mirror row_mask:0xf bank_mask:0xa
	v_fma_f32 v13, -v33, v41, v13
	s_nop 1
	v_mov_b32_dpp v41, v13 quad_perm:[2,2,2,2] row_mask:0xf bank_mask:0xf
	s_nop 1
	v_mov_b32_dpp v41, v41 row_half_mirror row_mask:0xf bank_mask:0xa
	v_fma_f32 v13, -v34, v41, v13
	s_nop 1
	v_mov_b32_dpp v41, v13 quad_perm:[3,3,3,3] row_mask:0xf bank_mask:0xf
	s_nop 1
	v_mov_b32_dpp v41, v41 row_half_mirror row_mask:0xf bank_mask:0xa
	v_fma_f32 v13, -v35, v41, v13
	s_nop 1
	v_mov_b32_dpp v41, v13 quad_perm:[0,0,0,0] row_mask:0xf bank_mask:0xf
	v_fma_f32 v13, -v36, v41, v13
	s_nop 1
	v_mov_b32_dpp v41, v13 quad_perm:[1,1,1,1] row_mask:0xf bank_mask:0xf
	v_fma_f32 v13, -v37, v41, v13
	s_nop 1
	v_mov_b32_dpp v41, v13 quad_perm:[2,2,2,2] row_mask:0xf bank_mask:0xf
	v_fma_f32 v13, -v38, v41, v13
	ds_read_b128 v[32:35], v40 offset:13248
	ds_read_b128 v[36:39], v40 offset:13264
	v_mul_f32_e32 v128, v4, v13
	v_mul_f32_e32 v129, v5, v13
	v_cvt_pk_bf16_f32 v128, v128, v128
	v_cvt_pk_bf16_f32 v129, v129, v129
	ds_write_b16 v2, v128 offset:5760
	ds_write_b16 v3, v129 offset:5760
	s_mov_b32 s91, 0
	v_cmp_ne_u32_e32 vcc, 0, v48
	s_nop 1
	v_cndmask_b32_e32 v46, v12, v13, vcc
	v_cndmask_b32_e32 v47, v13, v12, vcc
; #define LAS __attribute__((address_space(3)))
; __device__ __forceinline__ void dn_prep(const Params& p, LAS unsigned char* lds) {
;     ...
;             for (int i = 1; i < 64; ++i) {
; #pragma unroll
;                 for (int j4 = 8; j4 < (i + 3) / 4; ++j4) rhi[j4 - 8] = *(const LAS f32x4*)(Asz + i * 68 + j4 * 4);
;                 if (i + 1 < 64) {
; #pragma unroll
;                     for (int j4 = 0; j4 < ((i + 4) / 4 < 8 ? (i + 4) / 4 : 8); ++j4) rlo[(i + 1) & 1][j4] = *(const LAS f32x4*)(Asz + (i + 1) * 68 + j4 * 4);
;                 }
;                 float a0 = (lane == i) ? 1.f : 0.f, a1 = 0.f, a2 = 0.f, a3 = 0.f;
; #pragma unroll
;                 for (int j4 = 0; j4 < (i + 3) / 4; ++j4) {
;                     const f32x4 av = (j4 < 8) ? rlo[i & 1][j4 & 7] : rhi[(j4 - 8) & 7];
;                     if (j4 * 4 + 0 < i) a0 -= av[0] * T[j4 * 4 + 0];
;                     if (j4 * 4 + 1 < i) a1 -= av[1] * T[j4 * 4 + 1];
;                     if (j4 * 4 + 2 < i) a2 -= av[2] * T[j4 * 4 + 2];
;                     if (j4 * 4 + 3 < i) a3 -= av[3] * T[j4 * 4 + 3];
;                 }
;                 T[i] = (a0 + a1) + (a2 + a3);
.Lfs_b6:
	s_cmp_gt_u32 s1, 6
	s_cbranch_scc1 .Lfs_z6
	s_waitcnt lgkmcnt(4)
	v_mul_f32_e32 v24, v72, v42
	v_mul_f32_e32 v25, v79, v42
	v_mul_f32_e32 v26, v86, v42
	v_mul_f32_e32 v27, v93, v42
	v_mul_f32_e32 v28, v100, v42
	v_mul_f32_e32 v29, v107, v42
	v_mul_f32_e32 v30, v114, v42
	v_mul_f32_e32 v31, v121, v42
	v_fmac_f32_dpp v24, v72, v43 row_ror:8 row_mask:0xf bank_mask:0xf
	v_fmac_f32_dpp v25, v79, v43 row_ror:8 row_mask:0xf bank_mask:0xf
	v_fmac_f32_dpp v26, v86, v43 row_ror:8 row_mask:0xf bank_mask:0xf
	v_fmac_f32_dpp v27, v93, v43 row_ror:8 row_mask:0xf bank_mask:0xf
	v_fmac_f32_dpp v28, v100, v43 row_ror:8 row_mask:0xf bank_mask:0xf
	v_fmac_f32_dpp v29, v107, v43 row_ror:8 row_mask:0xf bank_mask:0xf
	v_fmac_f32_dpp v30, v114, v43 row_ror:8 row_mask:0xf bank_mask:0xf
	v_fmac_f32_dpp v31, v121, v43 row_ror:8 row_mask:0xf bank_mask:0xf
	v_fmac_f32_e32 v24, v74, v44
	v_fmac_f32_e32 v25, v81, v44
	v_fmac_f32_e32 v26, v88, v44
	v_fmac_f32_e32 v27, v95, v44
	v_fmac_f32_e32 v28, v102, v44
	v_fmac_f32_e32 v29, v109, v44
	v_fmac_f32_e32 v30, v116, v44
	v_fmac_f32_e32 v31, v123, v44
	v_fmac_f32_dpp v24, v74, v45 row_ror:8 row_mask:0xf bank_mask:0xf
	v_fmac_f32_dpp v25, v81, v45 row_ror:8 row_mask:0xf bank_mask:0xf
	v_fmac_f32_dpp v26, v88, v45 row_ror:8 row_mask:0xf bank_mask:0xf
	v_fmac_f32_dpp v27, v95, v45 row_ror:8 row_mask:0xf bank_mask:0xf
	v_fmac_f32_dpp v28, v102, v45 row_ror:8 row_mask:0xf bank_mask:0xf
	v_fmac_f32_dpp v29, v109, v45 row_ror:8 row_mask:0xf bank_mask:0xf
	v_fmac_f32_dpp v30, v116, v45 row_ror:8 row_mask:0xf bank_mask:0xf
	v_fmac_f32_dpp v31, v123, v45 row_ror:8 row_mask:0xf bank_mask:0xf
	v_fmac_f32_e32 v24, v76, v46
	v_fmac_f32_e32 v25, v83, v46
	v_fmac_f32_e32 v26, v90, v46
	v_fmac_f32_e32 v27, v97, v46
	v_fmac_f32_e32 v28, v104, v46
	v_fmac_f32_e32 v29, v111, v46
	v_fmac_f32_e32 v30, v118, v46
	v_fmac_f32_e32 v31, v125, v46
	v_fmac_f32_dpp v24, v76, v47 row_ror:8 row_mask:0xf bank_mask:0xf
	v_fmac_f32_dpp v25, v83, v47 row_ror:8 row_mask:0xf bank_mask:0xf
	v_fmac_f32_dpp v26, v90, v47 row_ror:8 row_mask:0xf bank_mask:0xf
	v_fmac_f32_dpp v27, v97, v47 row_ror:8 row_mask:0xf bank_mask:0xf
	v_fmac_f32_dpp v28, v104, v47 row_ror:8 row_mask:0xf bank_mask:0xf
	v_fmac_f32_dpp v29, v111, v47 row_ror:8 row_mask:0xf bank_mask:0xf
	v_fmac_f32_dpp v30, v118, v47 row_ror:8 row_mask:0xf bank_mask:0xf
	v_fmac_f32_dpp v31, v125, v47 row_ror:8 row_mask:0xf bank_mask:0xf
	v_add_f32_dpp v24, v24, v24 quad_perm:[1,0,3,2] row_mask:0xf bank_mask:0xf bound_ctrl:1
	v_add_f32_dpp v25, v25, v25 quad_perm:[1,0,3,2] row_mask:0xf bank_mask:0xf bound_ctrl:1
	v_add_f32_dpp v26, v26, v26 quad_perm:[1,0,3,2] row_mask:0xf bank_mask:0xf bound_ctrl:1
	v_add_f32_dpp v27, v27, v27 quad_perm:[1,0,3,2] row_mask:0xf bank_mask:0xf bound_ctrl:1
	v_add_f32_dpp v28, v28, v28 quad_perm:[1,0,3,2] row_mask:0xf bank_mask:0xf bound_ctrl:1
	v_add_f32_dpp v29, v29, v29 quad_perm:[1,0,3,2] row_mask:0xf bank_mask:0xf bound_ctrl:1
	v_add_f32_dpp v30, v30, v30 quad_perm:[1,0,3,2] row_mask:0xf bank_mask:0xf bound_ctrl:1
	v_add_f32_dpp v31, v31, v31 quad_perm:[1,0,3,2] row_mask:0xf bank_mask:0xf bound_ctrl:1
	v_add_f32_dpp v24, v24, v24 quad_perm:[2,3,0,1] row_mask:0xf bank_mask:0xf bound_ctrl:1
	v_add_f32_dpp v25, v25, v25 quad_perm:[2,3,0,1] row_mask:0xf bank_mask:0xf bound_ctrl:1
	v_add_f32_dpp v26, v26, v26 quad_perm:[2,3,0,1] row_mask:0xf bank_mask:0xf bound_ctrl:1
	v_add_f32_dpp v27, v27, v27 quad_perm:[2,3,0,1] row_mask:0xf bank_mask:0xf bound_ctrl:1
	v_add_f32_dpp v28, v28, v28 quad_perm:[2,3,0,1] row_mask:0xf bank_mask:0xf bound_ctrl:1
	v_add_f32_dpp v29, v29, v29 quad_perm:[2,3,0,1] row_mask:0xf bank_mask:0xf bound_ctrl:1
	v_add_f32_dpp v30, v30, v30 quad_perm:[2,3,0,1] row_mask:0xf bank_mask:0xf bound_ctrl:1
	v_add_f32_dpp v31, v31, v31 quad_perm:[2,3,0,1] row_mask:0xf bank_mask:0xf bound_ctrl:1
	v_add_f32_dpp v24, v24, v24 row_half_mirror row_mask:0xf bank_mask:0xf bound_ctrl:1
	v_add_f32_dpp v25, v25, v25 row_half_mirror row_mask:0xf bank_mask:0xf bound_ctrl:1
	v_add_f32_dpp v26, v26, v26 row_half_mirror row_mask:0xf bank_mask:0xf bound_ctrl:1
	v_add_f32_dpp v27, v27, v27 row_half_mirror row_mask:0xf bank_mask:0xf bound_ctrl:1
	v_add_f32_dpp v28, v28, v28 row_half_mirror row_mask:0xf bank_mask:0xf bound_ctrl:1
	v_add_f32_dpp v29, v29, v29 row_half_mirror row_mask:0xf bank_mask:0xf bound_ctrl:1
	v_add_f32_dpp v30, v30, v30 row_half_mirror row_mask:0xf bank_mask:0xf bound_ctrl:1
	v_add_f32_dpp v31, v31, v31 row_half_mirror row_mask:0xf bank_mask:0xf bound_ctrl:1
	v_fma_f32 v24, v16, s91, -v24
	v_fma_f32 v25, v17, s91, -v25
	v_fma_f32 v26, v18, s91, -v26
	v_fma_f32 v27, v19, s91, -v27
	v_fma_f32 v28, v20, s91, -v28
	v_fma_f32 v29, v21, s91, -v29
	v_fma_f32 v30, v22, s91, -v30
	v_fma_f32 v31, v23, s91, -v31
	s_waitcnt lgkmcnt(0)
; #define LAS __attribute__((address_space(3)))
; __device__ __forceinline__ bf16_t f2bf(float f) { return (bf16_t)(cvt_pk_bf16(f, 0.f) & 0xffffu); }
; __device__ __forceinline__ void dn_prep(const Params& p, LAS unsigned char* lds) {
;     ...
;                 for (int j4 = 8; j4 < (i + 3) / 4; ++j4) rhi[j4 - 8] = *(const LAS f32x4*)(Asz + i * 68 + j4 * 4);
;                 if (i + 1 < 64) {
; #pragma unroll
;                     for (int j4 = 0; j4 < ((i + 4) / 4 < 8 ? (i + 4) / 4 : 8); ++j4) rlo[(i + 1) & 1][j4] = *(const LAS f32x4*)(Asz + (i + 1) * 68 + j4 * 4);
;                 }
;                 float a0 = (lane == i) ? 1.f : 0.f, a1 = 0.f, a2 = 0.f, a3 = 0.f;
; #pragma unroll
;                 for (int j4 = 0; j4 < (i + 3) / 4; ++j4) {
;                     const f32x4 av = (j4 < 8) ? rlo[i & 1][j4 & 7] : rhi[(j4 - 8) & 7];
;                     if (j4 * 4 + 0 < i) a0 -= av[0] * T[j4 * 4 + 0];
;                     if (j4 * 4 + 1 < i) a1 -= av[1] * T[j4 * 4 + 1];
;                     if (j4 * 4 + 2 < i) a2 -= av[2] * T[j4 * 4 + 2];
;                     if (j4 * 4 + 3 < i) a3 -= av[3] * T[j4 * 4 + 3];
;                 }
;                 T[i] = (a0 + a1) + (a2 + a3);
;                 tub[i * 72] = f2bf(T[i] * bc); twb[i * 72] = f2bf(T[i] * wcf);
	ds_read_b32 v72, v49 offset:15232
	ds_read_b32 v74, v49 offset:15296
	ds_read_b32 v76, v49 offset:15360
	ds_read_b32 v78, v0 offset:15424
	ds_read_b32 v79, v49 offset:15504
	ds_read_b32 v81, v49 offset:15568
	ds_read_b32 v83, v49 offset:15632
	ds_read_b32 v85, v0 offset:15696
	ds_read_b32 v86, v49 offset:15776
	ds_read_b32 v88, v49 offset:15840
	ds_read_b32 v90, v49 offset:15904
	ds_read_b32 v92, v0 offset:15968
	ds_read_b32 v93, v49 offset:16048
	ds_read_b32 v95, v49 offset:16112
	ds_read_b32 v97, v49 offset:16176
	ds_read_b32 v99, v0 offset:16240
	ds_read_b32 v100, v49 offset:16320
	ds_read_b32 v102, v49 offset:16384
	ds_read_b32 v104, v49 offset:16448
	ds_read_b32 v106, v0 offset:16512
	ds_read_b32 v107, v49 offset:16592
	ds_read_b32 v109, v49 offset:16656
	ds_read_b32 v111, v49 offset:16720
	ds_read_b32 v113, v0 offset:16784
	ds_read_b32 v114, v49 offset:16864
	ds_read_b32 v116, v49 offset:16928
	ds_read_b32 v118, v49 offset:16992
	ds_read_b32 v120, v0 offset:17056
	ds_read_b32 v121, v49 offset:17136
	ds_read_b32 v123, v49 offset:17200
	ds_read_b32 v125, v49 offset:17264
	ds_read_b32 v127, v0 offset:17328
	v_mov_b32_e32 v14, v24
	v_cndmask_b32_e64 v14, v14, v25, s[6:7]
	v_cndmask_b32_e64 v14, v14, v26, s[68:69]
	v_cndmask_b32_e64 v14, v14, v27, s[92:93]
	v_cndmask_b32_e64 v14, v14, v28, s[94:95]
	v_cndmask_b32_e64 v14, v14, v29, s[96:97]
	v_cndmask_b32_e64 v14, v14, v30, s[98:99]
	v_cndmask_b32_e64 v14, v14, v31, s[100:101]
	s_nop 1
	v_mov_b32_dpp v41, v14 quad_perm:[0,0,0,0] row_mask:0xf bank_mask:0xf
	s_nop 1
	v_mov_b32_dpp v41, v41 row_half_mirror row_mask:0xf bank_mask:0xa
	v_fma_f32 v14, -v32, v41, v14
	s_nop 1
	v_mov_b32_dpp v41, v14 quad_perm:[1,1,1,1] row_mask:0xf bank_mask:0xf
	s_nop 1
	v_mov_b32_dpp v41, v41 row_half_mirror row_mask:0xf bank_mask:0xa
	v_fma_f32 v14, -v33, v41, v14
	s_nop 1
	v_mov_b32_dpp v41, v14 quad_perm:[2,2,2,2] row_mask:0xf bank_mask:0xf
	s_nop 1
	v_mov_b32_dpp v41, v41 row_half_mirror row_mask:0xf bank_mask:0xa
	v_fma_f32 v14, -v34, v41, v14
	s_nop 1
	v_mov_b32_dpp v41, v14 quad_perm:[3,3,3,3] row_mask:0xf bank_mask:0xf
	s_nop 1
	v_mov_b32_dpp v41, v41 row_half_mirror row_mask:0xf bank_mask:0xa
	v_fma_f32 v14, -v35, v41, v14
	s_nop 1
	v_mov_b32_dpp v41, v14 quad_perm:[0,0,0,0] row_mask:0xf bank_mask:0xf
	v_fma_f32 v14, -v36, v41, v14
	s_nop 1
	v_mov_b32_dpp v41, v14 quad_perm:[1,1,1,1] row_mask:0xf bank_mask:0xf
	v_fma_f32 v14, -v37, v41, v14
	s_nop 1
	v_mov_b32_dpp v41, v14 quad_perm:[2,2,2,2] row_mask:0xf bank_mask:0xf
	v_fma_f32 v14, -v38, v41, v14
	ds_read_b128 v[32:35], v40 offset:15456
	ds_read_b128 v[36:39], v40 offset:15472
	v_mul_f32_e32 v128, v4, v14
	v_mul_f32_e32 v129, v5, v14
	v_cvt_pk_bf16_f32 v128, v128, v128
	v_cvt_pk_bf16_f32 v129, v129, v129
	ds_write_b16 v2, v128 offset:6912
	ds_write_b16 v3, v129 offset:6912
	s_mov_b32 s91, 0
; #define LAS __attribute__((address_space(3)))
; __device__ __forceinline__ bf16_t f2bf(float f) { return (bf16_t)(cvt_pk_bf16(f, 0.f) & 0xffffu); }
; __device__ __forceinline__ void dn_prep(const Params& p, LAS unsigned char* lds) {
;     ...
;             for (int i = 1; i < 64; ++i) {
; #pragma unroll
;                 for (int j4 = 8; j4 < (i + 3) / 4; ++j4) rhi[j4 - 8] = *(const LAS f32x4*)(Asz + i * 68 + j4 * 4);
;                 if (i + 1 < 64) {
; #pragma unroll
;                     for (int j4 = 0; j4 < ((i + 4) / 4 < 8 ? (i + 4) / 4 : 8); ++j4) rlo[(i + 1) & 1][j4] = *(const LAS f32x4*)(Asz + (i + 1) * 68 + j4 * 4);
;                 }
;                 float a0 = (lane == i) ? 1.f : 0.f, a1 = 0.f, a2 = 0.f, a3 = 0.f;
; #pragma unroll
;                 for (int j4 = 0; j4 < (i + 3) / 4; ++j4) {
;                     const f32x4 av = (j4 < 8) ? rlo[i & 1][j4 & 7] : rhi[(j4 - 8) & 7];
;                     if (j4 * 4 + 0 < i) a0 -= av[0] * T[j4 * 4 + 0];
;                     if (j4 * 4 + 1 < i) a1 -= av[1] * T[j4 * 4 + 1];
;                     if (j4 * 4 + 2 < i) a2 -= av[2] * T[j4 * 4 + 2];
;                     if (j4 * 4 + 3 < i) a3 -= av[3] * T[j4 * 4 + 3];
;                 }
;                 T[i] = (a0 + a1) + (a2 + a3);
;                 tub[i * 72] = f2bf(T[i] * bc); twb[i * 72] = f2bf(T[i] * wcf);
;                 __builtin_amdgcn_sched_barrier(0);
.Lfs_b7:
	s_waitcnt lgkmcnt(4)
	v_mul_f32_e32 v24, v72, v42
	v_mul_f32_e32 v25, v79, v42
	v_mul_f32_e32 v26, v86, v42
	v_mul_f32_e32 v27, v93, v42
	v_mul_f32_e32 v28, v100, v42
	v_mul_f32_e32 v29, v107, v42
	v_mul_f32_e32 v30, v114, v42
	v_mul_f32_e32 v31, v121, v42
	v_fmac_f32_dpp v24, v72, v43 row_ror:8 row_mask:0xf bank_mask:0xf
	v_fmac_f32_dpp v25, v79, v43 row_ror:8 row_mask:0xf bank_mask:0xf
	v_fmac_f32_dpp v26, v86, v43 row_ror:8 row_mask:0xf bank_mask:0xf
	v_fmac_f32_dpp v27, v93, v43 row_ror:8 row_mask:0xf bank_mask:0xf
	v_fmac_f32_dpp v28, v100, v43 row_ror:8 row_mask:0xf bank_mask:0xf
	v_fmac_f32_dpp v29, v107, v43 row_ror:8 row_mask:0xf bank_mask:0xf
	v_fmac_f32_dpp v30, v114, v43 row_ror:8 row_mask:0xf bank_mask:0xf
	v_fmac_f32_dpp v31, v121, v43 row_ror:8 row_mask:0xf bank_mask:0xf
	v_fmac_f32_e32 v24, v74, v44
	v_fmac_f32_e32 v25, v81, v44
	v_fmac_f32_e32 v26, v88, v44
	v_fmac_f32_e32 v27, v95, v44
	v_fmac_f32_e32 v28, v102, v44
	v_fmac_f32_e32 v29, v109, v44
	v_fmac_f32_e32 v30, v116, v44
	v_fmac_f32_e32 v31, v123, v44
	v_fmac_f32_dpp v24, v74, v45 row_ror:8 row_mask:0xf bank_mask:0xf
	v_fmac_f32_dpp v25, v81, v45 row_ror:8 row_mask:0xf bank_mask:0xf
	v_fmac_f32_dpp v26, v88, v45 row_ror:8 row_mask:0xf bank_mask:0xf
	v_fmac_f32_dpp v27, v95, v45 row_ror:8 row_mask:0xf bank_mask:0xf
	v_fmac_f32_dpp v28, v102, v45 row_ror:8 row_mask:0xf bank_mask:0xf
	v_fmac_f32_dpp v29, v109, v45 row_ror:8 row_mask:0xf bank_mask:0xf
	v_fmac_f32_dpp v30, v116, v45 row_ror:8 row_mask:0xf bank_mask:0xf
	v_fmac_f32_dpp v31, v123, v45 row_ror:8 row_mask:0xf bank_mask:0xf
	v_fmac_f32_e32 v24, v76, v46
	v_fmac_f32_e32 v25, v83, v46
	v_fmac_f32_e32 v26, v90, v46
	v_fmac_f32_e32 v27, v97, v46
	v_fmac_f32_e32 v28, v104, v46
	v_fmac_f32_e32 v29, v111, v46
	v_fmac_f32_e32 v30, v118, v46
	v_fmac_f32_e32 v31, v125, v46
	v_fmac_f32_dpp v24, v76, v47 row_ror:8 row_mask:0xf bank_mask:0xf
	v_fmac_f32_dpp v25, v83, v47 row_ror:8 row_mask:0xf bank_mask:0xf
	v_fmac_f32_dpp v26, v90, v47 row_ror:8 row_mask:0xf bank_mask:0xf
	v_fmac_f32_dpp v27, v97, v47 row_ror:8 row_mask:0xf bank_mask:0xf
	v_fmac_f32_dpp v28, v104, v47 row_ror:8 row_mask:0xf bank_mask:0xf
	v_fmac_f32_dpp v29, v111, v47 row_ror:8 row_mask:0xf bank_mask:0xf
	v_fmac_f32_dpp v30, v118, v47 row_ror:8 row_mask:0xf bank_mask:0xf
	v_fmac_f32_dpp v31, v125, v47 row_ror:8 row_mask:0xf bank_mask:0xf
	v_fmac_f32_e32 v24, v78, v14
	v_fmac_f32_e32 v25, v85, v14
	v_fmac_f32_e32 v26, v92, v14
	v_fmac_f32_e32 v27, v99, v14
	v_fmac_f32_e32 v28, v106, v14
	v_fmac_f32_e32 v29, v113, v14
	v_fmac_f32_e32 v30, v120, v14
	v_fmac_f32_e32 v31, v127, v14
	v_add_f32_dpp v24, v24, v24 quad_perm:[1,0,3,2] row_mask:0xf bank_mask:0xf bound_ctrl:1
	v_add_f32_dpp v25, v25, v25 quad_perm:[1,0,3,2] row_mask:0xf bank_mask:0xf bound_ctrl:1
	v_add_f32_dpp v26, v26, v26 quad_perm:[1,0,3,2] row_mask:0xf bank_mask:0xf bound_ctrl:1
	v_add_f32_dpp v27, v27, v27 quad_perm:[1,0,3,2] row_mask:0xf bank_mask:0xf bound_ctrl:1
	v_add_f32_dpp v28, v28, v28 quad_perm:[1,0,3,2] row_mask:0xf bank_mask:0xf bound_ctrl:1
	v_add_f32_dpp v29, v29, v29 quad_perm:[1,0,3,2] row_mask:0xf bank_mask:0xf bound_ctrl:1
	v_add_f32_dpp v30, v30, v30 quad_perm:[1,0,3,2] row_mask:0xf bank_mask:0xf bound_ctrl:1
	v_add_f32_dpp v31, v31, v31 quad_perm:[1,0,3,2] row_mask:0xf bank_mask:0xf bound_ctrl:1
	v_add_f32_dpp v24, v24, v24 quad_perm:[2,3,0,1] row_mask:0xf bank_mask:0xf bound_ctrl:1
	v_add_f32_dpp v25, v25, v25 quad_perm:[2,3,0,1] row_mask:0xf bank_mask:0xf bound_ctrl:1
	v_add_f32_dpp v26, v26, v26 quad_perm:[2,3,0,1] row_mask:0xf bank_mask:0xf bound_ctrl:1
	v_add_f32_dpp v27, v27, v27 quad_perm:[2,3,0,1] row_mask:0xf bank_mask:0xf bound_ctrl:1
	v_add_f32_dpp v28, v28, v28 quad_perm:[2,3,0,1] row_mask:0xf bank_mask:0xf bound_ctrl:1
	v_add_f32_dpp v29, v29, v29 quad_perm:[2,3,0,1] row_mask:0xf bank_mask:0xf bound_ctrl:1
	v_add_f32_dpp v30, v30, v30 quad_perm:[2,3,0,1] row_mask:0xf bank_mask:0xf bound_ctrl:1
	v_add_f32_dpp v31, v31, v31 quad_perm:[2,3,0,1] row_mask:0xf bank_mask:0xf bound_ctrl:1
	v_add_f32_dpp v24, v24, v24 row_half_mirror row_mask:0xf bank_mask:0xf bound_ctrl:1
	v_add_f32_dpp v25, v25, v25 row_half_mirror row_mask:0xf bank_mask:0xf bound_ctrl:1
	v_add_f32_dpp v26, v26, v26 row_half_mirror row_mask:0xf bank_mask:0xf bound_ctrl:1
	v_add_f32_dpp v27, v27, v27 row_half_mirror row_mask:0xf bank_mask:0xf bound_ctrl:1
	v_add_f32_dpp v28, v28, v28 row_half_mirror row_mask:0xf bank_mask:0xf bound_ctrl:1
	v_add_f32_dpp v29, v29, v29 row_half_mirror row_mask:0xf bank_mask:0xf bound_ctrl:1
	v_add_f32_dpp v30, v30, v30 row_half_mirror row_mask:0xf bank_mask:0xf bound_ctrl:1
	v_add_f32_dpp v31, v31, v31 row_half_mirror row_mask:0xf bank_mask:0xf bound_ctrl:1
	v_fma_f32 v24, v16, s91, -v24
	v_fma_f32 v25, v17, s91, -v25
	v_fma_f32 v26, v18, s91, -v26
	v_fma_f32 v27, v19, s91, -v27
	v_fma_f32 v28, v20, s91, -v28
	v_fma_f32 v29, v21, s91, -v29
	v_fma_f32 v30, v22, s91, -v30
	v_fma_f32 v31, v23, s91, -v31
	s_waitcnt lgkmcnt(0)
	v_mov_b32_e32 v15, v24
	v_cndmask_b32_e64 v15, v15, v25, s[6:7]
	v_cndmask_b32_e64 v15, v15, v26, s[68:69]
	v_cndmask_b32_e64 v15, v15, v27, s[92:93]
	v_cndmask_b32_e64 v15, v15, v28, s[94:95]
	v_cndmask_b32_e64 v15, v15, v29, s[96:97]
	v_cndmask_b32_e64 v15, v15, v30, s[98:99]
	v_cndmask_b32_e64 v15, v15, v31, s[100:101]
	s_nop 1
	v_mov_b32_dpp v41, v15 quad_perm:[0,0,0,0] row_mask:0xf bank_mask:0xf
	s_nop 1
	v_mov_b32_dpp v41, v41 row_half_mirror row_mask:0xf bank_mask:0xa
	v_fma_f32 v15, -v32, v41, v15
	s_nop 1
	v_mov_b32_dpp v41, v15 quad_perm:[1,1,1,1] row_mask:0xf bank_mask:0xf
	s_nop 1
	v_mov_b32_dpp v41, v41 row_half_mirror row_mask:0xf bank_mask:0xa
	v_fma_f32 v15, -v33, v41, v15
	s_nop 1
	v_mov_b32_dpp v41, v15 quad_perm:[2,2,2,2] row_mask:0xf bank_mask:0xf
	s_nop 1
	v_mov_b32_dpp v41, v41 row_half_mirror row_mask:0xf bank_mask:0xa
	v_fma_f32 v15, -v34, v41, v15
	s_nop 1
	v_mov_b32_dpp v41, v15 quad_perm:[3,3,3,3] row_mask:0xf bank_mask:0xf
	s_nop 1
	v_mov_b32_dpp v41, v41 row_half_mirror row_mask:0xf bank_mask:0xa
	v_fma_f32 v15, -v35, v41, v15
	s_nop 1
	v_mov_b32_dpp v41, v15 quad_perm:[0,0,0,0] row_mask:0xf bank_mask:0xf
	v_fma_f32 v15, -v36, v41, v15
	s_nop 1
	v_mov_b32_dpp v41, v15 quad_perm:[1,1,1,1] row_mask:0xf bank_mask:0xf
	v_fma_f32 v15, -v37, v41, v15
	s_nop 1
	v_mov_b32_dpp v41, v15 quad_perm:[2,2,2,2] row_mask:0xf bank_mask:0xf
	v_fma_f32 v15, -v38, v41, v15
	v_mul_f32_e32 v128, v4, v15
	v_mul_f32_e32 v129, v5, v15
	v_cvt_pk_bf16_f32 v128, v128, v128
	v_cvt_pk_bf16_f32 v129, v129, v129
	ds_write_b16 v2, v128 offset:8064
	ds_write_b16 v3, v129 offset:8064
	s_mov_b32 s91, 0
	s_branch .LBB0_378

; #define LAS __attribute__((address_space(3)))
; __device__ __forceinline__ void dn_prep(const Params& p, LAS unsigned char* lds) {
;     ...
;                 for (int j4 = 8; j4 < (i + 3) / 4; ++j4) rhi[j4 - 8] = *(const LAS f32x4*)(Asz + i * 68 + j4 * 4);
;                 if (i + 1 < 64) {
; #pragma unroll
;                     for (int j4 = 0; j4 < ((i + 4) / 4 < 8 ? (i + 4) / 4 : 8); ++j4) rlo[(i + 1) & 1][j4] = *(const LAS f32x4*)(Asz + (i + 1) * 68 + j4 * 4);
;                 }
.Lfs_z1:
	s_cmp_eq_u32 s1, 2
	s_cbranch_scc0 .Lfs_zw1
	ds_read_b32 v72, v49 offset:4352
	ds_read_b32 v79, v49 offset:4624
	ds_read_b32 v86, v49 offset:4896
	ds_read_b32 v93, v49 offset:5168
	ds_read_b32 v100, v49 offset:5440
	ds_read_b32 v107, v49 offset:5712
	ds_read_b32 v114, v49 offset:5984
	ds_read_b32 v121, v49 offset:6256
	ds_read_b128 v[32:35], v40 offset:4416
	ds_read_b128 v[36:39], v40 offset:4432

; #define LAS __attribute__((address_space(3)))
; __device__ __forceinline__ void dn_prep(const Params& p, LAS unsigned char* lds) {
;     ...
;                 for (int j4 = 8; j4 < (i + 3) / 4; ++j4) rhi[j4 - 8] = *(const LAS f32x4*)(Asz + i * 68 + j4 * 4);
;                 if (i + 1 < 64) {
; #pragma unroll
;                     for (int j4 = 0; j4 < ((i + 4) / 4 < 8 ? (i + 4) / 4 : 8); ++j4) rlo[(i + 1) & 1][j4] = *(const LAS f32x4*)(Asz + (i + 1) * 68 + j4 * 4);
;                 }
.Lfs_z2:
	s_cmp_eq_u32 s1, 3
	s_cbranch_scc0 .Lfs_zw2
	ds_read_b32 v72, v49 offset:6528
	ds_read_b32 v74, v0 offset:6592
	ds_read_b32 v79, v49 offset:6800
	ds_read_b32 v81, v0 offset:6864
	ds_read_b32 v86, v49 offset:7072
	ds_read_b32 v88, v0 offset:7136
	ds_read_b32 v93, v49 offset:7344
	ds_read_b32 v95, v0 offset:7408
	ds_read_b32 v100, v49 offset:7616
	ds_read_b32 v102, v0 offset:7680
	ds_read_b32 v107, v49 offset:7888
	ds_read_b32 v109, v0 offset:7952
	ds_read_b32 v114, v49 offset:8160
	ds_read_b32 v116, v0 offset:8224
	ds_read_b32 v121, v49 offset:8432
	ds_read_b32 v123, v0 offset:8496
	ds_read_b128 v[32:35], v40 offset:6624
	ds_read_b128 v[36:39], v40 offset:6640

; #define LAS __attribute__((address_space(3)))
; __device__ __forceinline__ void dn_prep(const Params& p, LAS unsigned char* lds) {
;     ...
;                 for (int j4 = 8; j4 < (i + 3) / 4; ++j4) rhi[j4 - 8] = *(const LAS f32x4*)(Asz + i * 68 + j4 * 4);
;                 if (i + 1 < 64) {
; #pragma unroll
;                     for (int j4 = 0; j4 < ((i + 4) / 4 < 8 ? (i + 4) / 4 : 8); ++j4) rlo[(i + 1) & 1][j4] = *(const LAS f32x4*)(Asz + (i + 1) * 68 + j4 * 4);
;                 }
.Lfs_z3:
	s_cmp_eq_u32 s1, 4
	s_cbranch_scc0 .Lfs_zw3
	ds_read_b32 v72, v49 offset:8704
	ds_read_b32 v74, v49 offset:8768
	ds_read_b32 v79, v49 offset:8976
	ds_read_b32 v81, v49 offset:9040
	ds_read_b32 v86, v49 offset:9248
	ds_read_b32 v88, v49 offset:9312
	ds_read_b32 v93, v49 offset:9520
	ds_read_b32 v95, v49 offset:9584
	ds_read_b32 v100, v49 offset:9792
	ds_read_b32 v102, v49 offset:9856
	ds_read_b32 v107, v49 offset:10064
	ds_read_b32 v109, v49 offset:10128
	ds_read_b32 v114, v49 offset:10336
	ds_read_b32 v116, v49 offset:10400
	ds_read_b32 v121, v49 offset:10608
	ds_read_b32 v123, v49 offset:10672
	ds_read_b128 v[32:35], v40 offset:8832
	ds_read_b128 v[36:39], v40 offset:8848

; #define LAS __attribute__((address_space(3)))
; __device__ __forceinline__ void dn_prep(const Params& p, LAS unsigned char* lds) {
;     ...
;                 for (int j4 = 8; j4 < (i + 3) / 4; ++j4) rhi[j4 - 8] = *(const LAS f32x4*)(Asz + i * 68 + j4 * 4);
;                 if (i + 1 < 64) {
; #pragma unroll
;                     for (int j4 = 0; j4 < ((i + 4) / 4 < 8 ? (i + 4) / 4 : 8); ++j4) rlo[(i + 1) & 1][j4] = *(const LAS f32x4*)(Asz + (i + 1) * 68 + j4 * 4);
;                 }
.Lfs_z4:
	s_cmp_eq_u32 s1, 5
	s_cbranch_scc0 .Lfs_zw4
	ds_read_b32 v72, v49 offset:10880
	ds_read_b32 v74, v49 offset:10944
	ds_read_b32 v76, v0 offset:11008
	ds_read_b32 v79, v49 offset:11152
	ds_read_b32 v81, v49 offset:11216
	ds_read_b32 v83, v0 offset:11280
	ds_read_b32 v86, v49 offset:11424
	ds_read_b32 v88, v49 offset:11488
	ds_read_b32 v90, v0 offset:11552
	ds_read_b32 v93, v49 offset:11696
	ds_read_b32 v95, v49 offset:11760
	ds_read_b32 v97, v0 offset:11824
	ds_read_b32 v100, v49 offset:11968
	ds_read_b32 v102, v49 offset:12032
	ds_read_b32 v104, v0 offset:12096
	ds_read_b32 v107, v49 offset:12240
	ds_read_b32 v109, v49 offset:12304
	ds_read_b32 v111, v0 offset:12368
	ds_read_b32 v114, v49 offset:12512
	ds_read_b32 v116, v49 offset:12576
	ds_read_b32 v118, v0 offset:12640
	ds_read_b32 v121, v49 offset:12784
	ds_read_b32 v123, v49 offset:12848
	ds_read_b32 v125, v0 offset:12912
	ds_read_b128 v[32:35], v40 offset:11040
	ds_read_b128 v[36:39], v40 offset:11056

; #define LAS __attribute__((address_space(3)))
; __device__ __forceinline__ void dn_prep(const Params& p, LAS unsigned char* lds) {
;     ...
;                 for (int j4 = 8; j4 < (i + 3) / 4; ++j4) rhi[j4 - 8] = *(const LAS f32x4*)(Asz + i * 68 + j4 * 4);
;                 if (i + 1 < 64) {
; #pragma unroll
;                     for (int j4 = 0; j4 < ((i + 4) / 4 < 8 ? (i + 4) / 4 : 8); ++j4) rlo[(i + 1) & 1][j4] = *(const LAS f32x4*)(Asz + (i + 1) * 68 + j4 * 4);
;                 }
.Lfs_z5:
	s_cmp_eq_u32 s1, 6
	s_cbranch_scc0 .Lfs_zw5
	ds_read_b32 v72, v49 offset:13056
	ds_read_b32 v74, v49 offset:13120
	ds_read_b32 v76, v49 offset:13184
	ds_read_b32 v79, v49 offset:13328
	ds_read_b32 v81, v49 offset:13392
	ds_read_b32 v83, v49 offset:13456
	ds_read_b32 v86, v49 offset:13600
	ds_read_b32 v88, v49 offset:13664
	ds_read_b32 v90, v49 offset:13728
	ds_read_b32 v93, v49 offset:13872
	ds_read_b32 v95, v49 offset:13936
	ds_read_b32 v97, v49 offset:14000
	ds_read_b32 v100, v49 offset:14144
	ds_read_b32 v102, v49 offset:14208
	ds_read_b32 v104, v49 offset:14272
	ds_read_b32 v107, v49 offset:14416
	ds_read_b32 v109, v49 offset:14480
	ds_read_b32 v111, v49 offset:14544
	ds_read_b32 v114, v49 offset:14688
	ds_read_b32 v116, v49 offset:14752
	ds_read_b32 v118, v49 offset:14816
	ds_read_b32 v121, v49 offset:14960
	ds_read_b32 v123, v49 offset:15024
	ds_read_b32 v125, v49 offset:15088
	ds_read_b128 v[32:35], v40 offset:13248
	ds_read_b128 v[36:39], v40 offset:13264

; #define LAS __attribute__((address_space(3)))
; __device__ __forceinline__ void dn_prep(const Params& p, LAS unsigned char* lds) {
;     ...
;                 for (int j4 = 8; j4 < (i + 3) / 4; ++j4) rhi[j4 - 8] = *(const LAS f32x4*)(Asz + i * 68 + j4 * 4);
;                 if (i + 1 < 64) {
; #pragma unroll
;                     for (int j4 = 0; j4 < ((i + 4) / 4 < 8 ? (i + 4) / 4 : 8); ++j4) rlo[(i + 1) & 1][j4] = *(const LAS f32x4*)(Asz + (i + 1) * 68 + j4 * 4);
;                 }
.Lfs_z6:
	s_cmp_eq_u32 s1, 7
	s_cbranch_scc0 .Lfs_zw6
	ds_read_b32 v72, v49 offset:15232
	ds_read_b32 v74, v49 offset:15296
	ds_read_b32 v76, v49 offset:15360
	ds_read_b32 v78, v0 offset:15424
	ds_read_b32 v79, v49 offset:15504
	ds_read_b32 v81, v49 offset:15568
	ds_read_b32 v83, v49 offset:15632
	ds_read_b32 v85, v0 offset:15696
	ds_read_b32 v86, v49 offset:15776
	ds_read_b32 v88, v49 offset:15840
	ds_read_b32 v90, v49 offset:15904
	ds_read_b32 v92, v0 offset:15968
	ds_read_b32 v93, v49 offset:16048
	ds_read_b32 v95, v49 offset:16112
	ds_read_b32 v97, v49 offset:16176
	ds_read_b32 v99, v0 offset:16240
	ds_read_b32 v100, v49 offset:16320
	ds_read_b32 v102, v49 offset:16384
	ds_read_b32 v104, v49 offset:16448
	ds_read_b32 v106, v0 offset:16512
	ds_read_b32 v107, v49 offset:16592
	ds_read_b32 v109, v49 offset:16656
	ds_read_b32 v111, v49 offset:16720
	ds_read_b32 v113, v0 offset:16784
	ds_read_b32 v114, v49 offset:16864
	ds_read_b32 v116, v49 offset:16928
	ds_read_b32 v118, v49 offset:16992
	ds_read_b32 v120, v0 offset:17056
	ds_read_b32 v121, v49 offset:17136
	ds_read_b32 v123, v49 offset:17200
	ds_read_b32 v125, v49 offset:17264
	ds_read_b32 v127, v0 offset:17328
	ds_read_b128 v[32:35], v40 offset:15456
	ds_read_b128 v[36:39], v40 offset:15472
